# one static s_setprio 1 for waves 0-3 (leading GEMM half), per-phase priority flips removed
# speedup vs baseline: 1.0684x; 1.0039x over previous
_Z10fwd_kernel6Params:
	v_readfirstlane_b32 s98, v0
	s_nop 3
	s_and_b32 s98, s98, 0x3ff
	s_lshr_b32 s98, s98, 6
	s_cmp_ge_u32 s98, 4
	s_cbranch_scc1 .Lprio_done
	s_setprio 1
.Lprio_done:
	s_load_dwordx8 s[60:67], s[0:1], 0xa0
	s_load_dwordx8 s[12:19], s[0:1], 0x80
	s_load_dword s3, s[0:1], 0xc0
	s_add_u32 s4, s0, 0xb8
	s_addc_u32 s5, s1, 0
	v_and_b32_e32 v181, 0x3ff, v0
	v_cmp_gt_u32_e32 vcc, 2, v181
	s_waitcnt lgkmcnt(0)
	v_writelane_b32 v247, s3, 0
	v_writelane_b32 v247, s4, 1
	s_nop 1
	v_writelane_b32 v247, s5, 2
	s_and_saveexec_b64 s[4:5], vcc
	v_lshl_add_u32 v1, v181, 2, 0
	v_add_u32_e32 v1, 0x23fc0, v1
	v_mov_b32_e32 v2, 0
	ds_write_b32 v1, v2
	s_or_b64 exec, exec, s[4:5]
	s_load_dwordx16 s[44:59], s[0:1], 0x0
	s_load_dwordx16 s[68:83], s[0:1], 0x40
	s_add_u32 s0, s64, 0x80000
	s_addc_u32 s1, s65, 0
	s_waitcnt lgkmcnt(0)
	s_barrier
	v_writelane_b32 v247, s68, 3
	v_cmp_eq_u32_e64 s[4:5], 0, v181
	s_nop 0
	v_writelane_b32 v247, s69, 4
	v_writelane_b32 v247, s70, 5
	v_writelane_b32 v247, s71, 6
	v_writelane_b32 v247, s72, 7
	v_writelane_b32 v247, s73, 8
	v_writelane_b32 v247, s74, 9
	v_writelane_b32 v247, s75, 10
	v_writelane_b32 v247, s76, 11
	v_writelane_b32 v247, s77, 12
	v_writelane_b32 v247, s78, 13
	v_writelane_b32 v247, s79, 14
	v_writelane_b32 v247, s80, 15
	v_writelane_b32 v247, s81, 16
	v_writelane_b32 v247, s82, 17
	v_writelane_b32 v247, s83, 18
	v_writelane_b32 v247, s0, 19
	s_nop 1
	v_writelane_b32 v247, s1, 20
	s_getreg_b32 s0, hwreg(HW_REG_XCC_ID, 0, 4)
	s_and_b32 s0, s0, 15
	v_writelane_b32 v247, s0, 21
	s_mov_b64 s[0:1], exec
	v_writelane_b32 v247, s4, 22
	s_nop 1
	v_writelane_b32 v247, s5, 23
	s_and_b64 s[4:5], s[0:1], s[4:5]
	s_mov_b64 exec, s[4:5]
	s_cbranch_execz .LBB0_5
	s_mov_b64 s[4:5], exec
	v_mbcnt_lo_u32_b32 v1, s4, 0
	v_mbcnt_hi_u32_b32 v1, s5, v1
	v_cmp_eq_u32_e32 vcc, 0, v1
	s_and_b64 s[6:7], exec, vcc
	s_mov_b64 exec, s[6:7]
	s_cbranch_execz .LBB0_5
	v_readlane_b32 s3, v247, 21
	s_bcnt1_i32_b64 s4, s[4:5]
	s_lshl_b32 s3, s3, 8
	v_mov_b32_e32 v2, s4
	v_readlane_b32 s4, v247, 19
	v_mov_b32_e32 v1, s3
	v_readlane_b32 s5, v247, 20
	s_nop 4
	global_atomic_add v1, v2, s[4:5] offset:1024
	s_and_b32 s98, s2, 7
	s_lshl_b32 s98, s98, 2
	s_add_i32 s98, s98, 0x3600
	v_readlane_b32 s99, v247, 21
	v_mov_b32_e32 v1, s98
	s_lshl_b32 s99, 1, s99
	v_mov_b32_e32 v2, s99
	global_atomic_or v1, v2, s[4:5]

.LBB0_152:
	ds_read_b128 v[128:131], v192
	ds_read_b128 v[132:135], v192 offset:1024
	ds_read_b128 v[136:139], v192 offset:2048
	ds_read_b128 v[140:143], v192 offset:3072
	ds_read_b128 v[164:167], v193
	ds_read_b128 v[168:171], v193 offset:1024
	ds_read_b128 v[172:175], v193 offset:2048
	ds_read_b128 v[176:179], v193 offset:3072
	s_add_u32 s78, s70, 0xfffc0080
	s_addc_u32 s79, s71, -1
	s_cmp_eq_u32 s96, 12
	s_cselect_b32 s81, s11, s79
	s_cselect_b32 s80, s22, s78
	s_cselect_b32 s79, s35, s95
	s_cselect_b32 s78, s37, s94
	v_lshl_add_u64 v[228:229], s[70:71], 0, v[156:157]
	s_add_i32 m0, s82, 0xc000
	ds_read_b128 v[196:199], v194
	ds_read_b128 v[200:203], v194 offset:1024
	ds_read_b128 v[204:207], v194 offset:2048
	ds_read_b128 v[208:211], v194 offset:3072
	ds_read_b128 v[212:215], v194 offset:4096
	ds_read_b128 v[216:219], v194 offset:5120
	ds_read_b128 v[220:223], v194 offset:6144
	ds_read_b128 v[224:227], v194 offset:7168
	global_load_lds_dwordx4 v[228:229], off
	v_lshl_add_u64 v[228:229], s[70:71], 0, v[158:159]
	s_add_i32 m0, s82, 0xe000
	s_nop 0
	global_load_lds_dwordx4 v[228:229], off
	s_waitcnt vmcnt(8)
	s_waitcnt lgkmcnt(0)
	s_barrier
	s_waitcnt lgkmcnt(0)
	v_mfma_f32_16x16x32_bf16 v[124:127], v[128:131], v[196:199], v[124:127]
	v_mfma_f32_16x16x32_bf16 v[120:123], v[136:139], v[196:199], v[120:123]
	v_mfma_f32_16x16x32_bf16 v[108:111], v[128:131], v[204:207], v[108:111]
	v_mfma_f32_16x16x32_bf16 v[104:107], v[136:139], v[204:207], v[104:107]
	v_mfma_f32_16x16x32_bf16 v[92:95], v[128:131], v[212:215], v[92:95]
	v_mfma_f32_16x16x32_bf16 v[88:91], v[136:139], v[212:215], v[88:91]
	v_mfma_f32_16x16x32_bf16 v[76:79], v[128:131], v[220:223], v[76:79]
	v_mfma_f32_16x16x32_bf16 v[72:75], v[136:139], v[220:223], v[72:75]
	v_mfma_f32_16x16x32_bf16 v[124:127], v[132:135], v[200:203], v[124:127]
	v_mfma_f32_16x16x32_bf16 v[120:123], v[140:143], v[200:203], v[120:123]
	v_mfma_f32_16x16x32_bf16 v[108:111], v[132:135], v[208:211], v[108:111]
	v_mfma_f32_16x16x32_bf16 v[104:107], v[140:143], v[208:211], v[104:107]
	v_mfma_f32_16x16x32_bf16 v[92:95], v[132:135], v[216:219], v[92:95]
	v_mfma_f32_16x16x32_bf16 v[88:91], v[140:143], v[216:219], v[88:91]
	v_mfma_f32_16x16x32_bf16 v[76:79], v[132:135], v[224:227], v[76:79]
	v_mfma_f32_16x16x32_bf16 v[72:75], v[140:143], v[224:227], v[72:75]
	v_mfma_f32_16x16x32_bf16 v[116:119], v[164:167], v[196:199], v[116:119]
	v_mfma_f32_16x16x32_bf16 v[112:115], v[172:175], v[196:199], v[112:115]
	v_mfma_f32_16x16x32_bf16 v[100:103], v[164:167], v[204:207], v[100:103]
	v_mfma_f32_16x16x32_bf16 v[96:99], v[172:175], v[204:207], v[96:99]
	v_mfma_f32_16x16x32_bf16 v[84:87], v[164:167], v[212:215], v[84:87]
	v_mfma_f32_16x16x32_bf16 v[80:83], v[172:175], v[212:215], v[80:83]
	v_mfma_f32_16x16x32_bf16 v[68:71], v[164:167], v[220:223], v[68:71]
	v_mfma_f32_16x16x32_bf16 v[64:67], v[172:175], v[220:223], v[64:67]
	v_mfma_f32_16x16x32_bf16 v[116:119], v[168:171], v[200:203], v[116:119]
	v_mfma_f32_16x16x32_bf16 v[112:115], v[176:179], v[200:203], v[112:115]
	v_mfma_f32_16x16x32_bf16 v[100:103], v[168:171], v[208:211], v[100:103]
	v_mfma_f32_16x16x32_bf16 v[96:99], v[176:179], v[208:211], v[96:99]
	v_mfma_f32_16x16x32_bf16 v[84:87], v[168:171], v[216:219], v[84:87]
	v_mfma_f32_16x16x32_bf16 v[80:83], v[176:179], v[216:219], v[80:83]
	v_mfma_f32_16x16x32_bf16 v[68:71], v[168:171], v[224:227], v[68:71]
	v_mfma_f32_16x16x32_bf16 v[64:67], v[176:179], v[224:227], v[64:67]
	s_barrier
	s_add_i32 s97, s90, s33
	v_lshl_add_u64 v[228:229], s[78:79], 0, v[146:147]
	s_mov_b32 m0, s97
	ds_read_b128 v[196:199], v194 offset:16384
	ds_read_b128 v[200:203], v194 offset:17408
	ds_read_b128 v[204:207], v194 offset:18432
	ds_read_b128 v[208:211], v194 offset:19456
	ds_read_b128 v[212:215], v194 offset:20480
	ds_read_b128 v[216:219], v194 offset:21504
	ds_read_b128 v[220:223], v194 offset:22528
	ds_read_b128 v[224:227], v194 offset:23552
	global_load_lds_dwordx4 v[228:229], off
	s_add_i32 m0, s97, 0x2000
	s_add_u32 vcc_lo, s78, 0x40000
	v_lshl_add_u64 v[230:231], s[78:79], 0, v[150:151]
	s_addc_u32 vcc_hi, s79, 0
	s_add_i32 s97, s91, s33
	global_load_lds_dwordx4 v[230:231], off
	v_lshl_add_u64 v[232:233], vcc, 0, v[146:147]
	s_mov_b32 m0, s97
	v_lshl_add_u64 v[234:235], s[80:81], 0, v[148:149]
	global_load_lds_dwordx4 v[232:233], off
	v_lshl_add_u64 v[232:233], vcc, 0, v[150:151]
	s_add_i32 m0, s97, 0x2000
	s_nop 0
	global_load_lds_dwordx4 v[232:233], off
	v_lshl_add_u64 v[232:233], s[80:81], 0, v[144:145]
	s_mov_b32 m0, s82
	s_nop 0
	global_load_lds_dwordx4 v[232:233], off
	s_mov_b32 m0, s83
	s_nop 0
	global_load_lds_dwordx4 v[234:235], off
	s_waitcnt vmcnt(8)
	s_waitcnt lgkmcnt(0)
	s_barrier
	s_waitcnt lgkmcnt(0)
	v_mfma_f32_16x16x32_bf16 v[60:63], v[128:131], v[196:199], v[60:63]
	v_mfma_f32_16x16x32_bf16 v[56:59], v[136:139], v[196:199], v[56:59]
	v_mfma_f32_16x16x32_bf16 v[44:47], v[128:131], v[204:207], v[44:47]
	v_mfma_f32_16x16x32_bf16 v[40:43], v[136:139], v[204:207], v[40:43]
	v_mfma_f32_16x16x32_bf16 v[28:31], v[128:131], v[212:215], v[28:31]
	v_mfma_f32_16x16x32_bf16 v[24:27], v[136:139], v[212:215], v[24:27]
	v_mfma_f32_16x16x32_bf16 v[12:15], v[128:131], v[220:223], v[12:15]
	v_mfma_f32_16x16x32_bf16 v[8:11], v[136:139], v[220:223], v[8:11]
	v_mfma_f32_16x16x32_bf16 v[60:63], v[132:135], v[200:203], v[60:63]
	v_mfma_f32_16x16x32_bf16 v[56:59], v[140:143], v[200:203], v[56:59]
	v_mfma_f32_16x16x32_bf16 v[44:47], v[132:135], v[208:211], v[44:47]
	v_mfma_f32_16x16x32_bf16 v[40:43], v[140:143], v[208:211], v[40:43]
	v_mfma_f32_16x16x32_bf16 v[28:31], v[132:135], v[216:219], v[28:31]
	v_mfma_f32_16x16x32_bf16 v[24:27], v[140:143], v[216:219], v[24:27]
	v_mfma_f32_16x16x32_bf16 v[12:15], v[132:135], v[224:227], v[12:15]
	v_mfma_f32_16x16x32_bf16 v[8:11], v[140:143], v[224:227], v[8:11]
	v_mfma_f32_16x16x32_bf16 v[52:55], v[164:167], v[196:199], v[52:55]
	v_mfma_f32_16x16x32_bf16 v[48:51], v[172:175], v[196:199], v[48:51]
	v_mfma_f32_16x16x32_bf16 v[36:39], v[164:167], v[204:207], v[36:39]
	v_mfma_f32_16x16x32_bf16 v[32:35], v[172:175], v[204:207], v[32:35]
	v_mfma_f32_16x16x32_bf16 v[20:23], v[164:167], v[212:215], v[20:23]
	v_mfma_f32_16x16x32_bf16 v[16:19], v[172:175], v[212:215], v[16:19]
	v_mfma_f32_16x16x32_bf16 v[4:7], v[164:167], v[220:223], v[4:7]
	v_mfma_f32_16x16x32_bf16 v[0:3], v[172:175], v[220:223], v[0:3]
	v_mfma_f32_16x16x32_bf16 v[52:55], v[168:171], v[200:203], v[52:55]
	v_mfma_f32_16x16x32_bf16 v[48:51], v[176:179], v[200:203], v[48:51]
	v_mfma_f32_16x16x32_bf16 v[36:39], v[168:171], v[208:211], v[36:39]
	v_mfma_f32_16x16x32_bf16 v[32:35], v[176:179], v[208:211], v[32:35]
	v_mfma_f32_16x16x32_bf16 v[20:23], v[168:171], v[216:219], v[20:23]
	v_mfma_f32_16x16x32_bf16 v[16:19], v[176:179], v[216:219], v[16:19]
	v_mfma_f32_16x16x32_bf16 v[4:7], v[168:171], v[224:227], v[4:7]
	v_mfma_f32_16x16x32_bf16 v[0:3], v[176:179], v[224:227], v[0:3]
	s_barrier
	s_add_i32 s97, 0, 0x18000
	s_add_i32 vcc_lo, 0, 0x1c000
	v_add_u32_e32 v140, s97, v180
	v_add_u32_e32 v152, vcc_lo, v180
	ds_read_b128 v[128:131], v140
	ds_read_b128 v[132:135], v140 offset:1024
	ds_read_b128 v[136:139], v140 offset:2048
	ds_read_b128 v[140:143], v140 offset:3072
	ds_read_b128 v[164:167], v152
	ds_read_b128 v[168:171], v152 offset:1024
	ds_read_b128 v[172:175], v152 offset:2048
	ds_read_b128 v[176:179], v152 offset:3072
	s_add_u32 s80, s80, 0x40000
	s_addc_u32 s81, s81, 0
	s_mov_b32 m0, s84
	v_lshl_add_u64 v[236:237], s[80:81], 0, v[144:145]
	ds_read_b128 v[196:199], v194 offset:32768
	ds_read_b128 v[200:203], v194 offset:33792
	ds_read_b128 v[204:207], v194 offset:34816
	ds_read_b128 v[208:211], v194 offset:35840
	ds_read_b128 v[212:215], v194 offset:36864
	ds_read_b128 v[216:219], v194 offset:37888
	ds_read_b128 v[220:223], v194 offset:38912
	ds_read_b128 v[224:227], v194 offset:39936
	global_load_lds_dwordx4 v[236:237], off
	v_lshl_add_u64 v[236:237], s[80:81], 0, v[148:149]
	s_mov_b32 m0, s85
	s_nop 0
	global_load_lds_dwordx4 v[236:237], off
	s_waitcnt vmcnt(8)
	s_waitcnt lgkmcnt(0)
	s_barrier
	s_waitcnt lgkmcnt(0)
	v_mfma_f32_16x16x32_bf16 v[124:127], v[128:131], v[196:199], v[124:127]
	v_mfma_f32_16x16x32_bf16 v[120:123], v[136:139], v[196:199], v[120:123]
	v_mfma_f32_16x16x32_bf16 v[108:111], v[128:131], v[204:207], v[108:111]
	v_mfma_f32_16x16x32_bf16 v[104:107], v[136:139], v[204:207], v[104:107]
	v_mfma_f32_16x16x32_bf16 v[92:95], v[128:131], v[212:215], v[92:95]
	v_mfma_f32_16x16x32_bf16 v[88:91], v[136:139], v[212:215], v[88:91]
	v_mfma_f32_16x16x32_bf16 v[76:79], v[128:131], v[220:223], v[76:79]
	v_mfma_f32_16x16x32_bf16 v[72:75], v[136:139], v[220:223], v[72:75]
	v_mfma_f32_16x16x32_bf16 v[124:127], v[132:135], v[200:203], v[124:127]
	v_mfma_f32_16x16x32_bf16 v[120:123], v[140:143], v[200:203], v[120:123]
	v_mfma_f32_16x16x32_bf16 v[108:111], v[132:135], v[208:211], v[108:111]
	v_mfma_f32_16x16x32_bf16 v[104:107], v[140:143], v[208:211], v[104:107]
	v_mfma_f32_16x16x32_bf16 v[92:95], v[132:135], v[216:219], v[92:95]
	v_mfma_f32_16x16x32_bf16 v[88:91], v[140:143], v[216:219], v[88:91]
	v_mfma_f32_16x16x32_bf16 v[76:79], v[132:135], v[224:227], v[76:79]
	v_mfma_f32_16x16x32_bf16 v[72:75], v[140:143], v[224:227], v[72:75]
	v_mfma_f32_16x16x32_bf16 v[116:119], v[164:167], v[196:199], v[116:119]
	v_mfma_f32_16x16x32_bf16 v[112:115], v[172:175], v[196:199], v[112:115]
	v_mfma_f32_16x16x32_bf16 v[100:103], v[164:167], v[204:207], v[100:103]
	v_mfma_f32_16x16x32_bf16 v[96:99], v[172:175], v[204:207], v[96:99]
	v_mfma_f32_16x16x32_bf16 v[84:87], v[164:167], v[212:215], v[84:87]
	v_mfma_f32_16x16x32_bf16 v[80:83], v[172:175], v[212:215], v[80:83]
	v_mfma_f32_16x16x32_bf16 v[68:71], v[164:167], v[220:223], v[68:71]
	v_mfma_f32_16x16x32_bf16 v[64:67], v[172:175], v[220:223], v[64:67]
	v_mfma_f32_16x16x32_bf16 v[116:119], v[168:171], v[200:203], v[116:119]
	v_mfma_f32_16x16x32_bf16 v[112:115], v[176:179], v[200:203], v[112:115]
	v_mfma_f32_16x16x32_bf16 v[100:103], v[168:171], v[208:211], v[100:103]
	v_mfma_f32_16x16x32_bf16 v[96:99], v[176:179], v[208:211], v[96:99]
	v_mfma_f32_16x16x32_bf16 v[84:87], v[168:171], v[216:219], v[84:87]
	v_mfma_f32_16x16x32_bf16 v[80:83], v[176:179], v[216:219], v[80:83]
	v_mfma_f32_16x16x32_bf16 v[68:71], v[168:171], v[224:227], v[68:71]
	v_mfma_f32_16x16x32_bf16 v[64:67], v[176:179], v[224:227], v[64:67]
	s_barrier
	s_add_i32 s80, s97, s33
	v_lshl_add_u64 v[228:229], v[228:229], 0, s[26:27]
	s_mov_b32 m0, s80
	ds_read_b128 v[196:199], v194 offset:49152
	ds_read_b128 v[200:203], v194 offset:50176
	ds_read_b128 v[204:207], v194 offset:51200
	ds_read_b128 v[208:211], v194 offset:52224
	ds_read_b128 v[212:215], v194 offset:53248
	ds_read_b128 v[216:219], v194 offset:54272
	ds_read_b128 v[220:223], v194 offset:55296
	ds_read_b128 v[224:227], v194 offset:56320
	global_load_lds_dwordx4 v[228:229], off
	s_add_i32 m0, s80, 0x2000
	s_add_u32 s78, s78, 0x40080
	v_lshl_add_u64 v[228:229], v[230:231], 0, s[26:27]
	s_addc_u32 s79, s79, 0
	s_add_i32 s80, vcc_lo, s33
	global_load_lds_dwordx4 v[228:229], off
	v_lshl_add_u64 v[228:229], s[78:79], 0, v[146:147]
	s_mov_b32 m0, s80
	s_nop 0
	global_load_lds_dwordx4 v[228:229], off
	v_lshl_add_u64 v[228:229], s[78:79], 0, v[150:151]
	s_add_i32 m0, s80, 0x2000
	s_nop 0
	global_load_lds_dwordx4 v[228:229], off
	v_lshl_add_u64 v[228:229], v[232:233], 0, s[26:27]
	s_mov_b32 m0, s87
	s_nop 0
	global_load_lds_dwordx4 v[228:229], off
	v_lshl_add_u64 v[228:229], v[234:235], 0, s[26:27]
	s_mov_b32 m0, s88
	s_nop 0
	global_load_lds_dwordx4 v[228:229], off
	s_waitcnt vmcnt(8)
	s_waitcnt lgkmcnt(0)
	s_barrier
	s_waitcnt lgkmcnt(0)
	v_mfma_f32_16x16x32_bf16 v[60:63], v[128:131], v[196:199], v[60:63]
	v_mfma_f32_16x16x32_bf16 v[56:59], v[136:139], v[196:199], v[56:59]
	v_mfma_f32_16x16x32_bf16 v[44:47], v[128:131], v[204:207], v[44:47]
	v_mfma_f32_16x16x32_bf16 v[40:43], v[136:139], v[204:207], v[40:43]
	v_mfma_f32_16x16x32_bf16 v[28:31], v[128:131], v[212:215], v[28:31]
	v_mfma_f32_16x16x32_bf16 v[24:27], v[136:139], v[212:215], v[24:27]
	v_mfma_f32_16x16x32_bf16 v[12:15], v[128:131], v[220:223], v[12:15]
	v_mfma_f32_16x16x32_bf16 v[8:11], v[136:139], v[220:223], v[8:11]
	v_mfma_f32_16x16x32_bf16 v[60:63], v[132:135], v[200:203], v[60:63]
	v_mfma_f32_16x16x32_bf16 v[56:59], v[140:143], v[200:203], v[56:59]
	v_mfma_f32_16x16x32_bf16 v[44:47], v[132:135], v[208:211], v[44:47]
	v_mfma_f32_16x16x32_bf16 v[40:43], v[140:143], v[208:211], v[40:43]
	v_mfma_f32_16x16x32_bf16 v[28:31], v[132:135], v[216:219], v[28:31]
	v_mfma_f32_16x16x32_bf16 v[24:27], v[140:143], v[216:219], v[24:27]
	v_mfma_f32_16x16x32_bf16 v[12:15], v[132:135], v[224:227], v[12:15]
	v_mfma_f32_16x16x32_bf16 v[8:11], v[140:143], v[224:227], v[8:11]
	v_mfma_f32_16x16x32_bf16 v[52:55], v[164:167], v[196:199], v[52:55]
	v_mfma_f32_16x16x32_bf16 v[48:51], v[172:175], v[196:199], v[48:51]
	v_mfma_f32_16x16x32_bf16 v[36:39], v[164:167], v[204:207], v[36:39]
	v_mfma_f32_16x16x32_bf16 v[32:35], v[172:175], v[204:207], v[32:35]
	v_mfma_f32_16x16x32_bf16 v[20:23], v[164:167], v[212:215], v[20:23]
	v_mfma_f32_16x16x32_bf16 v[16:19], v[172:175], v[212:215], v[16:19]
	v_mfma_f32_16x16x32_bf16 v[4:7], v[164:167], v[220:223], v[4:7]
	v_mfma_f32_16x16x32_bf16 v[0:3], v[172:175], v[220:223], v[0:3]
	v_mfma_f32_16x16x32_bf16 v[52:55], v[168:171], v[200:203], v[52:55]
	v_mfma_f32_16x16x32_bf16 v[48:51], v[176:179], v[200:203], v[48:51]
	v_mfma_f32_16x16x32_bf16 v[36:39], v[168:171], v[208:211], v[36:39]
	v_mfma_f32_16x16x32_bf16 v[32:35], v[176:179], v[208:211], v[32:35]
	v_mfma_f32_16x16x32_bf16 v[20:23], v[168:171], v[216:219], v[20:23]
	v_mfma_f32_16x16x32_bf16 v[16:19], v[176:179], v[216:219], v[16:19]
	v_mfma_f32_16x16x32_bf16 v[4:7], v[168:171], v[224:227], v[4:7]
	v_mfma_f32_16x16x32_bf16 v[0:3], v[176:179], v[224:227], v[0:3]
	s_barrier
	s_add_i32 s96, s96, 2
	s_add_u32 s70, s70, 0x100
	s_addc_u32 s71, s71, 0
	s_add_u32 s94, s94, 0x100
	s_addc_u32 s95, s95, 0
	s_cmp_gt_u32 s96, 13
	s_cbranch_scc0 .LBB0_152
	s_and_b64 vcc, exec, s[28:29]
	s_cbranch_vccz .LBB0_155
	s_barrier

.LBB0_617:
	ds_read_b128 v[144:147], v151
	ds_read_b128 v[156:159], v151 offset:1024
	ds_read_b128 v[160:163], v151 offset:2048
	ds_read_b128 v[164:167], v151 offset:3072
	ds_read_b128 v[168:171], v152
	ds_read_b128 v[172:175], v152 offset:1024
	ds_read_b128 v[176:179], v152 offset:2048
	ds_read_b128 v[184:187], v152 offset:3072
	s_add_u32 s26, s24, 0xfffc0080
	s_addc_u32 s27, s25, -1
	s_cmp_eq_u32 s51, 12
	s_cselect_b32 s29, s17, s27
	s_cselect_b32 s28, s23, s26
	s_cselect_b32 s27, s15, s50
	s_cselect_b32 s26, s46, s47
	v_lshl_add_u64 v[220:221], s[24:25], 0, v[136:137]
	s_add_i32 m0, s34, 0xc000
	ds_read_b128 v[188:191], v153
	ds_read_b128 v[192:195], v153 offset:1024
	ds_read_b128 v[196:199], v153 offset:2048
	ds_read_b128 v[200:203], v153 offset:3072
	ds_read_b128 v[204:207], v153 offset:4096
	ds_read_b128 v[208:211], v153 offset:5120
	ds_read_b128 v[212:215], v153 offset:6144
	ds_read_b128 v[216:219], v153 offset:7168
	global_load_lds_dwordx4 v[220:221], off
	v_lshl_add_u64 v[220:221], s[24:25], 0, v[138:139]
	s_add_i32 m0, s34, 0xe000
	s_nop 0
	global_load_lds_dwordx4 v[220:221], off
	s_waitcnt vmcnt(8)
	s_waitcnt lgkmcnt(0)
	s_barrier
	s_waitcnt lgkmcnt(0)
	v_mfma_f32_16x16x32_bf16 v[124:127], v[144:147], v[188:191], v[124:127]
	v_mfma_f32_16x16x32_bf16 v[120:123], v[160:163], v[188:191], v[120:123]
	v_mfma_f32_16x16x32_bf16 v[108:111], v[144:147], v[196:199], v[108:111]
	v_mfma_f32_16x16x32_bf16 v[104:107], v[160:163], v[196:199], v[104:107]
	v_mfma_f32_16x16x32_bf16 v[92:95], v[144:147], v[204:207], v[92:95]
	v_mfma_f32_16x16x32_bf16 v[88:91], v[160:163], v[204:207], v[88:91]
	v_mfma_f32_16x16x32_bf16 v[76:79], v[144:147], v[212:215], v[76:79]
	v_mfma_f32_16x16x32_bf16 v[72:75], v[160:163], v[212:215], v[72:75]
	v_mfma_f32_16x16x32_bf16 v[124:127], v[156:159], v[192:195], v[124:127]
	v_mfma_f32_16x16x32_bf16 v[120:123], v[164:167], v[192:195], v[120:123]
	v_mfma_f32_16x16x32_bf16 v[108:111], v[156:159], v[200:203], v[108:111]
	v_mfma_f32_16x16x32_bf16 v[104:107], v[164:167], v[200:203], v[104:107]
	v_mfma_f32_16x16x32_bf16 v[92:95], v[156:159], v[208:211], v[92:95]
	v_mfma_f32_16x16x32_bf16 v[88:91], v[164:167], v[208:211], v[88:91]
	v_mfma_f32_16x16x32_bf16 v[76:79], v[156:159], v[216:219], v[76:79]
	v_mfma_f32_16x16x32_bf16 v[72:75], v[164:167], v[216:219], v[72:75]
	v_mfma_f32_16x16x32_bf16 v[116:119], v[168:171], v[188:191], v[116:119]
	v_mfma_f32_16x16x32_bf16 v[112:115], v[176:179], v[188:191], v[112:115]
	v_mfma_f32_16x16x32_bf16 v[100:103], v[168:171], v[196:199], v[100:103]
	v_mfma_f32_16x16x32_bf16 v[96:99], v[176:179], v[196:199], v[96:99]
	v_mfma_f32_16x16x32_bf16 v[84:87], v[168:171], v[204:207], v[84:87]
	v_mfma_f32_16x16x32_bf16 v[80:83], v[176:179], v[204:207], v[80:83]
	v_mfma_f32_16x16x32_bf16 v[68:71], v[168:171], v[212:215], v[68:71]
	v_mfma_f32_16x16x32_bf16 v[64:67], v[176:179], v[212:215], v[64:67]
	v_mfma_f32_16x16x32_bf16 v[116:119], v[172:175], v[192:195], v[116:119]
	v_mfma_f32_16x16x32_bf16 v[112:115], v[184:187], v[192:195], v[112:115]
	v_mfma_f32_16x16x32_bf16 v[100:103], v[172:175], v[200:203], v[100:103]
	v_mfma_f32_16x16x32_bf16 v[96:99], v[184:187], v[200:203], v[96:99]
	v_mfma_f32_16x16x32_bf16 v[84:87], v[172:175], v[208:211], v[84:87]
	v_mfma_f32_16x16x32_bf16 v[80:83], v[184:187], v[208:211], v[80:83]
	v_mfma_f32_16x16x32_bf16 v[68:71], v[172:175], v[216:219], v[68:71]
	v_mfma_f32_16x16x32_bf16 v[64:67], v[184:187], v[216:219], v[64:67]
	s_barrier
	s_add_i32 s52, s41, s33
	v_lshl_add_u64 v[220:221], s[26:27], 0, v[130:131]
	s_mov_b32 m0, s52
	ds_read_b128 v[188:191], v153 offset:16384
	ds_read_b128 v[192:195], v153 offset:17408
	ds_read_b128 v[196:199], v153 offset:18432
	ds_read_b128 v[200:203], v153 offset:19456
	ds_read_b128 v[204:207], v153 offset:20480
	ds_read_b128 v[208:211], v153 offset:21504
	ds_read_b128 v[212:215], v153 offset:22528
	ds_read_b128 v[216:219], v153 offset:23552
	global_load_lds_dwordx4 v[220:221], off
	s_add_i32 m0, s52, 0x2000
	s_add_u32 s52, s26, 0x40000
	v_lshl_add_u64 v[222:223], s[26:27], 0, v[134:135]
	s_addc_u32 s53, s27, 0
	s_add_i32 s54, s42, s33
	global_load_lds_dwordx4 v[222:223], off
	v_lshl_add_u64 v[224:225], s[52:53], 0, v[130:131]
	s_mov_b32 m0, s54
	v_lshl_add_u64 v[226:227], s[28:29], 0, v[132:133]
	global_load_lds_dwordx4 v[224:225], off
	v_lshl_add_u64 v[224:225], s[52:53], 0, v[134:135]
	s_add_i32 m0, s54, 0x2000
	s_nop 0
	global_load_lds_dwordx4 v[224:225], off
	v_lshl_add_u64 v[224:225], s[28:29], 0, v[128:129]
	s_mov_b32 m0, s34
	s_nop 0
	global_load_lds_dwordx4 v[224:225], off
	s_mov_b32 m0, s35
	s_nop 0
	global_load_lds_dwordx4 v[226:227], off
	s_waitcnt vmcnt(8)
	s_waitcnt lgkmcnt(0)
	s_barrier
	s_waitcnt lgkmcnt(0)
	v_mfma_f32_16x16x32_bf16 v[60:63], v[144:147], v[188:191], v[60:63]
	v_mfma_f32_16x16x32_bf16 v[56:59], v[160:163], v[188:191], v[56:59]
	v_mfma_f32_16x16x32_bf16 v[44:47], v[144:147], v[196:199], v[44:47]
	v_mfma_f32_16x16x32_bf16 v[40:43], v[160:163], v[196:199], v[40:43]
	v_mfma_f32_16x16x32_bf16 v[28:31], v[144:147], v[204:207], v[28:31]
	v_mfma_f32_16x16x32_bf16 v[24:27], v[160:163], v[204:207], v[24:27]
	v_mfma_f32_16x16x32_bf16 v[12:15], v[144:147], v[212:215], v[12:15]
	v_mfma_f32_16x16x32_bf16 v[8:11], v[160:163], v[212:215], v[8:11]
	v_mfma_f32_16x16x32_bf16 v[60:63], v[156:159], v[192:195], v[60:63]
	v_mfma_f32_16x16x32_bf16 v[56:59], v[164:167], v[192:195], v[56:59]
	v_mfma_f32_16x16x32_bf16 v[44:47], v[156:159], v[200:203], v[44:47]
	v_mfma_f32_16x16x32_bf16 v[40:43], v[164:167], v[200:203], v[40:43]
	v_mfma_f32_16x16x32_bf16 v[28:31], v[156:159], v[208:211], v[28:31]
	v_mfma_f32_16x16x32_bf16 v[24:27], v[164:167], v[208:211], v[24:27]
	v_mfma_f32_16x16x32_bf16 v[12:15], v[156:159], v[216:219], v[12:15]
	v_mfma_f32_16x16x32_bf16 v[8:11], v[164:167], v[216:219], v[8:11]
	v_mfma_f32_16x16x32_bf16 v[52:55], v[168:171], v[188:191], v[52:55]
	v_mfma_f32_16x16x32_bf16 v[48:51], v[176:179], v[188:191], v[48:51]
	v_mfma_f32_16x16x32_bf16 v[36:39], v[168:171], v[196:199], v[36:39]
	v_mfma_f32_16x16x32_bf16 v[32:35], v[176:179], v[196:199], v[32:35]
	v_mfma_f32_16x16x32_bf16 v[20:23], v[168:171], v[204:207], v[20:23]
	v_mfma_f32_16x16x32_bf16 v[16:19], v[176:179], v[204:207], v[16:19]
	v_mfma_f32_16x16x32_bf16 v[4:7], v[168:171], v[212:215], v[4:7]
	v_mfma_f32_16x16x32_bf16 v[0:3], v[176:179], v[212:215], v[0:3]
	v_mfma_f32_16x16x32_bf16 v[52:55], v[172:175], v[192:195], v[52:55]
	v_mfma_f32_16x16x32_bf16 v[48:51], v[184:187], v[192:195], v[48:51]
	v_mfma_f32_16x16x32_bf16 v[36:39], v[172:175], v[200:203], v[36:39]
	v_mfma_f32_16x16x32_bf16 v[32:35], v[184:187], v[200:203], v[32:35]
	v_mfma_f32_16x16x32_bf16 v[20:23], v[172:175], v[208:211], v[20:23]
	v_mfma_f32_16x16x32_bf16 v[16:19], v[184:187], v[208:211], v[16:19]
	v_mfma_f32_16x16x32_bf16 v[4:7], v[172:175], v[216:219], v[4:7]
	v_mfma_f32_16x16x32_bf16 v[0:3], v[184:187], v[216:219], v[0:3]
	s_barrier
	s_add_i32 s52, 0, 0x18000
	v_add_u32_e32 v155, s52, v149
	s_add_i32 s53, 0, 0x1c000
	ds_read_b128 v[144:147], v155
	ds_read_b128 v[156:159], v155 offset:1024
	ds_read_b128 v[160:163], v155 offset:2048
	ds_read_b128 v[164:167], v155 offset:3072
	v_add_u32_e32 v155, s53, v149
	ds_read_b128 v[168:171], v155
	ds_read_b128 v[172:175], v155 offset:1024
	ds_read_b128 v[176:179], v155 offset:2048
	ds_read_b128 v[184:187], v155 offset:3072
	s_add_u32 s28, s28, 0x40000
	s_addc_u32 s29, s29, 0
	s_mov_b32 m0, s36
	v_lshl_add_u64 v[228:229], s[28:29], 0, v[128:129]
	ds_read_b128 v[188:191], v153 offset:32768
	ds_read_b128 v[192:195], v153 offset:33792
	ds_read_b128 v[196:199], v153 offset:34816
	ds_read_b128 v[200:203], v153 offset:35840
	ds_read_b128 v[204:207], v153 offset:36864
	ds_read_b128 v[208:211], v153 offset:37888
	ds_read_b128 v[212:215], v153 offset:38912
	ds_read_b128 v[216:219], v153 offset:39936
	global_load_lds_dwordx4 v[228:229], off
	v_lshl_add_u64 v[228:229], s[28:29], 0, v[132:133]
	s_mov_b32 m0, s37
	s_nop 0
	global_load_lds_dwordx4 v[228:229], off
	s_waitcnt vmcnt(8)
	s_waitcnt lgkmcnt(0)
	s_barrier
	s_waitcnt lgkmcnt(0)
	v_mfma_f32_16x16x32_bf16 v[124:127], v[144:147], v[188:191], v[124:127]
	v_mfma_f32_16x16x32_bf16 v[120:123], v[160:163], v[188:191], v[120:123]
	v_mfma_f32_16x16x32_bf16 v[108:111], v[144:147], v[196:199], v[108:111]
	v_mfma_f32_16x16x32_bf16 v[104:107], v[160:163], v[196:199], v[104:107]
	v_mfma_f32_16x16x32_bf16 v[92:95], v[144:147], v[204:207], v[92:95]
	v_mfma_f32_16x16x32_bf16 v[88:91], v[160:163], v[204:207], v[88:91]
	v_mfma_f32_16x16x32_bf16 v[76:79], v[144:147], v[212:215], v[76:79]
	v_mfma_f32_16x16x32_bf16 v[72:75], v[160:163], v[212:215], v[72:75]
	v_mfma_f32_16x16x32_bf16 v[124:127], v[156:159], v[192:195], v[124:127]
	v_mfma_f32_16x16x32_bf16 v[120:123], v[164:167], v[192:195], v[120:123]
	v_mfma_f32_16x16x32_bf16 v[108:111], v[156:159], v[200:203], v[108:111]
	v_mfma_f32_16x16x32_bf16 v[104:107], v[164:167], v[200:203], v[104:107]
	v_mfma_f32_16x16x32_bf16 v[92:95], v[156:159], v[208:211], v[92:95]
	v_mfma_f32_16x16x32_bf16 v[88:91], v[164:167], v[208:211], v[88:91]
	v_mfma_f32_16x16x32_bf16 v[76:79], v[156:159], v[216:219], v[76:79]
	v_mfma_f32_16x16x32_bf16 v[72:75], v[164:167], v[216:219], v[72:75]
	v_mfma_f32_16x16x32_bf16 v[116:119], v[168:171], v[188:191], v[116:119]
	v_mfma_f32_16x16x32_bf16 v[112:115], v[176:179], v[188:191], v[112:115]
	v_mfma_f32_16x16x32_bf16 v[100:103], v[168:171], v[196:199], v[100:103]
	v_mfma_f32_16x16x32_bf16 v[96:99], v[176:179], v[196:199], v[96:99]
	v_mfma_f32_16x16x32_bf16 v[84:87], v[168:171], v[204:207], v[84:87]
	v_mfma_f32_16x16x32_bf16 v[80:83], v[176:179], v[204:207], v[80:83]
	v_mfma_f32_16x16x32_bf16 v[68:71], v[168:171], v[212:215], v[68:71]
	v_mfma_f32_16x16x32_bf16 v[64:67], v[176:179], v[212:215], v[64:67]
	v_mfma_f32_16x16x32_bf16 v[116:119], v[172:175], v[192:195], v[116:119]
	v_mfma_f32_16x16x32_bf16 v[112:115], v[184:187], v[192:195], v[112:115]
	v_mfma_f32_16x16x32_bf16 v[100:103], v[172:175], v[200:203], v[100:103]
	v_mfma_f32_16x16x32_bf16 v[96:99], v[184:187], v[200:203], v[96:99]
	v_mfma_f32_16x16x32_bf16 v[84:87], v[172:175], v[208:211], v[84:87]
	v_mfma_f32_16x16x32_bf16 v[80:83], v[184:187], v[208:211], v[80:83]
	v_mfma_f32_16x16x32_bf16 v[68:71], v[172:175], v[216:219], v[68:71]
	v_mfma_f32_16x16x32_bf16 v[64:67], v[184:187], v[216:219], v[64:67]
	s_barrier
	s_add_i32 s28, s52, s33
	v_lshl_add_u64 v[220:221], v[220:221], 0, s[10:11]
	s_mov_b32 m0, s28
	ds_read_b128 v[188:191], v153 offset:49152
	ds_read_b128 v[192:195], v153 offset:50176
	ds_read_b128 v[196:199], v153 offset:51200
	ds_read_b128 v[200:203], v153 offset:52224
	ds_read_b128 v[204:207], v153 offset:53248
	ds_read_b128 v[208:211], v153 offset:54272
	ds_read_b128 v[212:215], v153 offset:55296
	ds_read_b128 v[216:219], v153 offset:56320
	global_load_lds_dwordx4 v[220:221], off
	s_add_i32 m0, s28, 0x2000
	s_add_u32 s26, s26, 0x40080
	v_lshl_add_u64 v[220:221], v[222:223], 0, s[10:11]
	s_addc_u32 s27, s27, 0
	s_add_i32 s28, s53, s33
	global_load_lds_dwordx4 v[220:221], off
	v_lshl_add_u64 v[220:221], s[26:27], 0, v[130:131]
	s_mov_b32 m0, s28
	s_nop 0
	global_load_lds_dwordx4 v[220:221], off
	v_lshl_add_u64 v[220:221], s[26:27], 0, v[134:135]
	s_add_i32 m0, s28, 0x2000
	s_nop 0
	global_load_lds_dwordx4 v[220:221], off
	v_lshl_add_u64 v[220:221], v[224:225], 0, s[10:11]
	s_mov_b32 m0, s39
	s_nop 0
	global_load_lds_dwordx4 v[220:221], off
	v_lshl_add_u64 v[220:221], v[226:227], 0, s[10:11]
	s_mov_b32 m0, s40
	s_nop 0
	global_load_lds_dwordx4 v[220:221], off
	s_waitcnt vmcnt(8)
	s_waitcnt lgkmcnt(0)
	s_barrier
	s_waitcnt lgkmcnt(0)
	v_mfma_f32_16x16x32_bf16 v[60:63], v[144:147], v[188:191], v[60:63]
	v_mfma_f32_16x16x32_bf16 v[56:59], v[160:163], v[188:191], v[56:59]
	v_mfma_f32_16x16x32_bf16 v[44:47], v[144:147], v[196:199], v[44:47]
	v_mfma_f32_16x16x32_bf16 v[40:43], v[160:163], v[196:199], v[40:43]
	v_mfma_f32_16x16x32_bf16 v[28:31], v[144:147], v[204:207], v[28:31]
	v_mfma_f32_16x16x32_bf16 v[24:27], v[160:163], v[204:207], v[24:27]
	v_mfma_f32_16x16x32_bf16 v[12:15], v[144:147], v[212:215], v[12:15]
	v_mfma_f32_16x16x32_bf16 v[8:11], v[160:163], v[212:215], v[8:11]
	v_mfma_f32_16x16x32_bf16 v[60:63], v[156:159], v[192:195], v[60:63]
	v_mfma_f32_16x16x32_bf16 v[56:59], v[164:167], v[192:195], v[56:59]
	v_mfma_f32_16x16x32_bf16 v[44:47], v[156:159], v[200:203], v[44:47]
	v_mfma_f32_16x16x32_bf16 v[40:43], v[164:167], v[200:203], v[40:43]
	v_mfma_f32_16x16x32_bf16 v[28:31], v[156:159], v[208:211], v[28:31]
	v_mfma_f32_16x16x32_bf16 v[24:27], v[164:167], v[208:211], v[24:27]
	v_mfma_f32_16x16x32_bf16 v[12:15], v[156:159], v[216:219], v[12:15]
	v_mfma_f32_16x16x32_bf16 v[8:11], v[164:167], v[216:219], v[8:11]
	v_mfma_f32_16x16x32_bf16 v[52:55], v[168:171], v[188:191], v[52:55]
	v_mfma_f32_16x16x32_bf16 v[48:51], v[176:179], v[188:191], v[48:51]
	v_mfma_f32_16x16x32_bf16 v[36:39], v[168:171], v[196:199], v[36:39]
	v_mfma_f32_16x16x32_bf16 v[32:35], v[176:179], v[196:199], v[32:35]
	v_mfma_f32_16x16x32_bf16 v[20:23], v[168:171], v[204:207], v[20:23]
	v_mfma_f32_16x16x32_bf16 v[16:19], v[176:179], v[204:207], v[16:19]
	v_mfma_f32_16x16x32_bf16 v[4:7], v[168:171], v[212:215], v[4:7]
	v_mfma_f32_16x16x32_bf16 v[0:3], v[176:179], v[212:215], v[0:3]
	v_mfma_f32_16x16x32_bf16 v[52:55], v[172:175], v[192:195], v[52:55]
	v_mfma_f32_16x16x32_bf16 v[48:51], v[184:187], v[192:195], v[48:51]
	v_mfma_f32_16x16x32_bf16 v[36:39], v[172:175], v[200:203], v[36:39]
	v_mfma_f32_16x16x32_bf16 v[32:35], v[184:187], v[200:203], v[32:35]
	v_mfma_f32_16x16x32_bf16 v[20:23], v[172:175], v[208:211], v[20:23]
	v_mfma_f32_16x16x32_bf16 v[16:19], v[184:187], v[208:211], v[16:19]
	v_mfma_f32_16x16x32_bf16 v[4:7], v[172:175], v[216:219], v[4:7]
	v_mfma_f32_16x16x32_bf16 v[0:3], v[184:187], v[216:219], v[0:3]
	s_barrier
	s_add_i32 s51, s51, 2
	s_add_u32 s24, s24, 0x100
	s_addc_u32 s25, s25, 0
	s_add_u32 s47, s47, 0x100
	s_addc_u32 s50, s50, 0
	s_cmp_gt_u32 s51, 13
	s_cbranch_scc0 .LBB0_617
	s_and_b64 vcc, exec, s[12:13]
	s_cbranch_vccz .LBB0_620
	s_barrier

.LBB0_705:
	ds_read_b128 v[154:157], v151
	ds_read_b128 v[158:161], v151 offset:1024
	ds_read_b128 v[162:165], v151 offset:2048
	ds_read_b128 v[166:169], v151 offset:3072
	ds_read_b128 v[170:173], v152
	ds_read_b128 v[174:177], v152 offset:1024
	ds_read_b128 v[184:187], v152 offset:2048
	ds_read_b128 v[188:191], v152 offset:3072
	s_add_u32 s22, s20, 0xfffc0080
	s_addc_u32 s23, s21, -1
	s_cmp_eq_u32 s50, 12
	s_cselect_b32 s25, s13, s23
	s_cselect_b32 s24, s42, s22
	s_cselect_b32 s23, s11, s47
	s_cselect_b32 s22, s43, s46
	v_lshl_add_u64 v[178:179], s[20:21], 0, v[136:137]
	s_add_i32 m0, s19, 0xc000
	ds_read_b128 v[192:195], v153
	ds_read_b128 v[196:199], v153 offset:1024
	ds_read_b128 v[200:203], v153 offset:2048
	ds_read_b128 v[204:207], v153 offset:3072
	ds_read_b128 v[208:211], v153 offset:4096
	ds_read_b128 v[212:215], v153 offset:5120
	ds_read_b128 v[216:219], v153 offset:6144
	ds_read_b128 v[220:223], v153 offset:7168
	global_load_lds_dwordx4 v[178:179], off
	v_lshl_add_u64 v[178:179], s[20:21], 0, v[138:139]
	s_add_i32 m0, s19, 0xe000
	s_nop 0
	global_load_lds_dwordx4 v[178:179], off
	s_waitcnt vmcnt(8)
	s_waitcnt lgkmcnt(0)
	s_barrier
	s_waitcnt lgkmcnt(0)
	v_mfma_f32_16x16x32_bf16 v[124:127], v[154:157], v[192:195], v[124:127]
	v_mfma_f32_16x16x32_bf16 v[116:119], v[162:165], v[192:195], v[116:119]
	v_mfma_f32_16x16x32_bf16 v[108:111], v[154:157], v[200:203], v[108:111]
	v_mfma_f32_16x16x32_bf16 v[100:103], v[162:165], v[200:203], v[100:103]
	v_mfma_f32_16x16x32_bf16 v[92:95], v[154:157], v[208:211], v[92:95]
	v_mfma_f32_16x16x32_bf16 v[84:87], v[162:165], v[208:211], v[84:87]
	v_mfma_f32_16x16x32_bf16 v[76:79], v[154:157], v[216:219], v[76:79]
	v_mfma_f32_16x16x32_bf16 v[68:71], v[162:165], v[216:219], v[68:71]
	v_mfma_f32_16x16x32_bf16 v[124:127], v[158:161], v[196:199], v[124:127]
	v_mfma_f32_16x16x32_bf16 v[116:119], v[166:169], v[196:199], v[116:119]
	v_mfma_f32_16x16x32_bf16 v[108:111], v[158:161], v[204:207], v[108:111]
	v_mfma_f32_16x16x32_bf16 v[100:103], v[166:169], v[204:207], v[100:103]
	v_mfma_f32_16x16x32_bf16 v[92:95], v[158:161], v[212:215], v[92:95]
	v_mfma_f32_16x16x32_bf16 v[84:87], v[166:169], v[212:215], v[84:87]
	v_mfma_f32_16x16x32_bf16 v[76:79], v[158:161], v[220:223], v[76:79]
	v_mfma_f32_16x16x32_bf16 v[68:71], v[166:169], v[220:223], v[68:71]
	v_mfma_f32_16x16x32_bf16 v[120:123], v[170:173], v[192:195], v[120:123]
	v_mfma_f32_16x16x32_bf16 v[112:115], v[184:187], v[192:195], v[112:115]
	v_mfma_f32_16x16x32_bf16 v[104:107], v[170:173], v[200:203], v[104:107]
	v_mfma_f32_16x16x32_bf16 v[96:99], v[184:187], v[200:203], v[96:99]
	v_mfma_f32_16x16x32_bf16 v[88:91], v[170:173], v[208:211], v[88:91]
	v_mfma_f32_16x16x32_bf16 v[80:83], v[184:187], v[208:211], v[80:83]
	v_mfma_f32_16x16x32_bf16 v[72:75], v[170:173], v[216:219], v[72:75]
	v_mfma_f32_16x16x32_bf16 v[64:67], v[184:187], v[216:219], v[64:67]
	v_mfma_f32_16x16x32_bf16 v[120:123], v[174:177], v[196:199], v[120:123]
	v_mfma_f32_16x16x32_bf16 v[112:115], v[188:191], v[196:199], v[112:115]
	v_mfma_f32_16x16x32_bf16 v[104:107], v[174:177], v[204:207], v[104:107]
	v_mfma_f32_16x16x32_bf16 v[96:99], v[188:191], v[204:207], v[96:99]
	v_mfma_f32_16x16x32_bf16 v[88:91], v[174:177], v[212:215], v[88:91]
	v_mfma_f32_16x16x32_bf16 v[80:83], v[188:191], v[212:215], v[80:83]
	v_mfma_f32_16x16x32_bf16 v[72:75], v[174:177], v[220:223], v[72:75]
	v_mfma_f32_16x16x32_bf16 v[64:67], v[188:191], v[220:223], v[64:67]
	s_barrier
	s_add_i32 s51, s36, s28
	v_lshl_add_u64 v[178:179], s[22:23], 0, v[132:133]
	s_mov_b32 m0, s51
	ds_read_b128 v[192:195], v153 offset:16384
	ds_read_b128 v[196:199], v153 offset:17408
	ds_read_b128 v[200:203], v153 offset:18432
	ds_read_b128 v[204:207], v153 offset:19456
	ds_read_b128 v[208:211], v153 offset:20480
	ds_read_b128 v[212:215], v153 offset:21504
	ds_read_b128 v[216:219], v153 offset:22528
	ds_read_b128 v[220:223], v153 offset:23552
	global_load_lds_dwordx4 v[178:179], off
	s_add_i32 m0, s51, 0x2000
	s_add_u32 s52, s22, 0x40000
	v_lshl_add_u64 v[224:225], s[22:23], 0, v[128:129]
	s_addc_u32 s53, s23, 0
	s_add_i32 s51, s37, s28
	global_load_lds_dwordx4 v[224:225], off
	v_lshl_add_u64 v[226:227], s[52:53], 0, v[132:133]
	s_mov_b32 m0, s51
	v_lshl_add_u64 v[228:229], s[24:25], 0, v[130:131]
	global_load_lds_dwordx4 v[226:227], off
	v_lshl_add_u64 v[226:227], s[52:53], 0, v[128:129]
	s_add_i32 m0, s51, 0x2000
	s_nop 0
	global_load_lds_dwordx4 v[226:227], off
	v_lshl_add_u64 v[226:227], s[24:25], 0, v[134:135]
	s_mov_b32 m0, s19
	s_nop 0
	global_load_lds_dwordx4 v[226:227], off
	s_mov_b32 m0, s30
	s_nop 0
	global_load_lds_dwordx4 v[228:229], off
	s_waitcnt vmcnt(8)
	s_waitcnt lgkmcnt(0)
	s_barrier
	s_waitcnt lgkmcnt(0)
	v_mfma_f32_16x16x32_bf16 v[60:63], v[154:157], v[192:195], v[60:63]
	v_mfma_f32_16x16x32_bf16 v[52:55], v[162:165], v[192:195], v[52:55]
	v_mfma_f32_16x16x32_bf16 v[44:47], v[154:157], v[200:203], v[44:47]
	v_mfma_f32_16x16x32_bf16 v[36:39], v[162:165], v[200:203], v[36:39]
	v_mfma_f32_16x16x32_bf16 v[28:31], v[154:157], v[208:211], v[28:31]
	v_mfma_f32_16x16x32_bf16 v[20:23], v[162:165], v[208:211], v[20:23]
	v_mfma_f32_16x16x32_bf16 v[12:15], v[154:157], v[216:219], v[12:15]
	v_mfma_f32_16x16x32_bf16 v[4:7], v[162:165], v[216:219], v[4:7]
	v_mfma_f32_16x16x32_bf16 v[60:63], v[158:161], v[196:199], v[60:63]
	v_mfma_f32_16x16x32_bf16 v[52:55], v[166:169], v[196:199], v[52:55]
	v_mfma_f32_16x16x32_bf16 v[44:47], v[158:161], v[204:207], v[44:47]
	v_mfma_f32_16x16x32_bf16 v[36:39], v[166:169], v[204:207], v[36:39]
	v_mfma_f32_16x16x32_bf16 v[28:31], v[158:161], v[212:215], v[28:31]
	v_mfma_f32_16x16x32_bf16 v[20:23], v[166:169], v[212:215], v[20:23]
	v_mfma_f32_16x16x32_bf16 v[12:15], v[158:161], v[220:223], v[12:15]
	v_mfma_f32_16x16x32_bf16 v[4:7], v[166:169], v[220:223], v[4:7]
	v_mfma_f32_16x16x32_bf16 v[56:59], v[170:173], v[192:195], v[56:59]
	v_mfma_f32_16x16x32_bf16 v[48:51], v[184:187], v[192:195], v[48:51]
	v_mfma_f32_16x16x32_bf16 v[40:43], v[170:173], v[200:203], v[40:43]
	v_mfma_f32_16x16x32_bf16 v[32:35], v[184:187], v[200:203], v[32:35]
	v_mfma_f32_16x16x32_bf16 v[24:27], v[170:173], v[208:211], v[24:27]
	v_mfma_f32_16x16x32_bf16 v[16:19], v[184:187], v[208:211], v[16:19]
	v_mfma_f32_16x16x32_bf16 v[8:11], v[170:173], v[216:219], v[8:11]
	v_mfma_f32_16x16x32_bf16 v[0:3], v[184:187], v[216:219], v[0:3]
	v_mfma_f32_16x16x32_bf16 v[56:59], v[174:177], v[196:199], v[56:59]
	v_mfma_f32_16x16x32_bf16 v[48:51], v[188:191], v[196:199], v[48:51]
	v_mfma_f32_16x16x32_bf16 v[40:43], v[174:177], v[204:207], v[40:43]
	v_mfma_f32_16x16x32_bf16 v[32:35], v[188:191], v[204:207], v[32:35]
	v_mfma_f32_16x16x32_bf16 v[24:27], v[174:177], v[212:215], v[24:27]
	v_mfma_f32_16x16x32_bf16 v[16:19], v[188:191], v[212:215], v[16:19]
	v_mfma_f32_16x16x32_bf16 v[8:11], v[174:177], v[220:223], v[8:11]
	v_mfma_f32_16x16x32_bf16 v[0:3], v[188:191], v[220:223], v[0:3]
	s_barrier
	s_add_i32 s51, 0, 0x18000
	s_add_i32 s52, 0, 0x1c000
	v_add_u32_e32 v166, s51, v145
	v_add_u32_e32 v180, s52, v145
	ds_read_b128 v[154:157], v166
	ds_read_b128 v[158:161], v166 offset:1024
	ds_read_b128 v[162:165], v166 offset:2048
	ds_read_b128 v[166:169], v166 offset:3072
	ds_read_b128 v[170:173], v180
	ds_read_b128 v[174:177], v180 offset:1024
	ds_read_b128 v[184:187], v180 offset:2048
	ds_read_b128 v[188:191], v180 offset:3072
	s_add_u32 s24, s24, 0x40000
	s_addc_u32 s25, s25, 0
	s_mov_b32 m0, s31
	v_lshl_add_u64 v[230:231], s[24:25], 0, v[134:135]
	ds_read_b128 v[192:195], v153 offset:32768
	ds_read_b128 v[196:199], v153 offset:33792
	ds_read_b128 v[200:203], v153 offset:34816
	ds_read_b128 v[204:207], v153 offset:35840
	ds_read_b128 v[208:211], v153 offset:36864
	ds_read_b128 v[212:215], v153 offset:37888
	ds_read_b128 v[216:219], v153 offset:38912
	ds_read_b128 v[220:223], v153 offset:39936
	global_load_lds_dwordx4 v[230:231], off
	v_lshl_add_u64 v[230:231], s[24:25], 0, v[130:131]
	s_mov_b32 m0, s33
	s_nop 0
	global_load_lds_dwordx4 v[230:231], off
	s_waitcnt vmcnt(8)
	s_waitcnt lgkmcnt(0)
	s_barrier
	s_waitcnt lgkmcnt(0)
	v_mfma_f32_16x16x32_bf16 v[124:127], v[154:157], v[192:195], v[124:127]
	v_mfma_f32_16x16x32_bf16 v[116:119], v[162:165], v[192:195], v[116:119]
	v_mfma_f32_16x16x32_bf16 v[108:111], v[154:157], v[200:203], v[108:111]
	v_mfma_f32_16x16x32_bf16 v[100:103], v[162:165], v[200:203], v[100:103]
	v_mfma_f32_16x16x32_bf16 v[92:95], v[154:157], v[208:211], v[92:95]
	v_mfma_f32_16x16x32_bf16 v[84:87], v[162:165], v[208:211], v[84:87]
	v_mfma_f32_16x16x32_bf16 v[76:79], v[154:157], v[216:219], v[76:79]
	v_mfma_f32_16x16x32_bf16 v[68:71], v[162:165], v[216:219], v[68:71]
	v_mfma_f32_16x16x32_bf16 v[124:127], v[158:161], v[196:199], v[124:127]
	v_mfma_f32_16x16x32_bf16 v[116:119], v[166:169], v[196:199], v[116:119]
	v_mfma_f32_16x16x32_bf16 v[108:111], v[158:161], v[204:207], v[108:111]
	v_mfma_f32_16x16x32_bf16 v[100:103], v[166:169], v[204:207], v[100:103]
	v_mfma_f32_16x16x32_bf16 v[92:95], v[158:161], v[212:215], v[92:95]
	v_mfma_f32_16x16x32_bf16 v[84:87], v[166:169], v[212:215], v[84:87]
	v_mfma_f32_16x16x32_bf16 v[76:79], v[158:161], v[220:223], v[76:79]
	v_mfma_f32_16x16x32_bf16 v[68:71], v[166:169], v[220:223], v[68:71]
	v_mfma_f32_16x16x32_bf16 v[120:123], v[170:173], v[192:195], v[120:123]
	v_mfma_f32_16x16x32_bf16 v[112:115], v[184:187], v[192:195], v[112:115]
	v_mfma_f32_16x16x32_bf16 v[104:107], v[170:173], v[200:203], v[104:107]
	v_mfma_f32_16x16x32_bf16 v[96:99], v[184:187], v[200:203], v[96:99]
	v_mfma_f32_16x16x32_bf16 v[88:91], v[170:173], v[208:211], v[88:91]
	v_mfma_f32_16x16x32_bf16 v[80:83], v[184:187], v[208:211], v[80:83]
	v_mfma_f32_16x16x32_bf16 v[72:75], v[170:173], v[216:219], v[72:75]
	v_mfma_f32_16x16x32_bf16 v[64:67], v[184:187], v[216:219], v[64:67]
	v_mfma_f32_16x16x32_bf16 v[120:123], v[174:177], v[196:199], v[120:123]
	v_mfma_f32_16x16x32_bf16 v[112:115], v[188:191], v[196:199], v[112:115]
	v_mfma_f32_16x16x32_bf16 v[104:107], v[174:177], v[204:207], v[104:107]
	v_mfma_f32_16x16x32_bf16 v[96:99], v[188:191], v[204:207], v[96:99]
	v_mfma_f32_16x16x32_bf16 v[88:91], v[174:177], v[212:215], v[88:91]
	v_mfma_f32_16x16x32_bf16 v[80:83], v[188:191], v[212:215], v[80:83]
	v_mfma_f32_16x16x32_bf16 v[72:75], v[174:177], v[220:223], v[72:75]
	v_mfma_f32_16x16x32_bf16 v[64:67], v[188:191], v[220:223], v[64:67]
	s_barrier
	s_add_i32 s24, s51, s28
	v_lshl_add_u64 v[178:179], v[178:179], 0, s[6:7]
	s_mov_b32 m0, s24
	ds_read_b128 v[192:195], v153 offset:49152
	ds_read_b128 v[196:199], v153 offset:50176
	ds_read_b128 v[200:203], v153 offset:51200
	ds_read_b128 v[204:207], v153 offset:52224
	ds_read_b128 v[208:211], v153 offset:53248
	ds_read_b128 v[212:215], v153 offset:54272
	ds_read_b128 v[216:219], v153 offset:55296
	ds_read_b128 v[220:223], v153 offset:56320
	global_load_lds_dwordx4 v[178:179], off
	s_add_i32 m0, s24, 0x2000
	s_add_u32 s22, s22, 0x40080
	v_lshl_add_u64 v[178:179], v[224:225], 0, s[6:7]
	s_addc_u32 s23, s23, 0
	s_add_i32 s24, s52, s28
	global_load_lds_dwordx4 v[178:179], off
	v_lshl_add_u64 v[178:179], s[22:23], 0, v[132:133]
	s_mov_b32 m0, s24
	s_nop 0
	global_load_lds_dwordx4 v[178:179], off
	v_lshl_add_u64 v[178:179], s[22:23], 0, v[128:129]
	s_add_i32 m0, s24, 0x2000
	s_nop 0
	global_load_lds_dwordx4 v[178:179], off
	v_lshl_add_u64 v[178:179], v[226:227], 0, s[6:7]
	s_mov_b32 m0, s34
	s_nop 0
	global_load_lds_dwordx4 v[178:179], off
	v_lshl_add_u64 v[178:179], v[228:229], 0, s[6:7]
	s_mov_b32 m0, s35
	s_nop 0
	global_load_lds_dwordx4 v[178:179], off
	s_waitcnt vmcnt(8)
	s_waitcnt lgkmcnt(0)
	s_barrier
	s_waitcnt lgkmcnt(0)
	v_mfma_f32_16x16x32_bf16 v[60:63], v[154:157], v[192:195], v[60:63]
	v_mfma_f32_16x16x32_bf16 v[52:55], v[162:165], v[192:195], v[52:55]
	v_mfma_f32_16x16x32_bf16 v[44:47], v[154:157], v[200:203], v[44:47]
	v_mfma_f32_16x16x32_bf16 v[36:39], v[162:165], v[200:203], v[36:39]
	v_mfma_f32_16x16x32_bf16 v[28:31], v[154:157], v[208:211], v[28:31]
	v_mfma_f32_16x16x32_bf16 v[20:23], v[162:165], v[208:211], v[20:23]
	v_mfma_f32_16x16x32_bf16 v[12:15], v[154:157], v[216:219], v[12:15]
	v_mfma_f32_16x16x32_bf16 v[4:7], v[162:165], v[216:219], v[4:7]
	v_mfma_f32_16x16x32_bf16 v[60:63], v[158:161], v[196:199], v[60:63]
	v_mfma_f32_16x16x32_bf16 v[52:55], v[166:169], v[196:199], v[52:55]
	v_mfma_f32_16x16x32_bf16 v[44:47], v[158:161], v[204:207], v[44:47]
	v_mfma_f32_16x16x32_bf16 v[36:39], v[166:169], v[204:207], v[36:39]
	v_mfma_f32_16x16x32_bf16 v[28:31], v[158:161], v[212:215], v[28:31]
	v_mfma_f32_16x16x32_bf16 v[20:23], v[166:169], v[212:215], v[20:23]
	v_mfma_f32_16x16x32_bf16 v[12:15], v[158:161], v[220:223], v[12:15]
	v_mfma_f32_16x16x32_bf16 v[4:7], v[166:169], v[220:223], v[4:7]
	v_mfma_f32_16x16x32_bf16 v[56:59], v[170:173], v[192:195], v[56:59]
	v_mfma_f32_16x16x32_bf16 v[48:51], v[184:187], v[192:195], v[48:51]
	v_mfma_f32_16x16x32_bf16 v[40:43], v[170:173], v[200:203], v[40:43]
	v_mfma_f32_16x16x32_bf16 v[32:35], v[184:187], v[200:203], v[32:35]
	v_mfma_f32_16x16x32_bf16 v[24:27], v[170:173], v[208:211], v[24:27]
	v_mfma_f32_16x16x32_bf16 v[16:19], v[184:187], v[208:211], v[16:19]
	v_mfma_f32_16x16x32_bf16 v[8:11], v[170:173], v[216:219], v[8:11]
	v_mfma_f32_16x16x32_bf16 v[0:3], v[184:187], v[216:219], v[0:3]
	v_mfma_f32_16x16x32_bf16 v[56:59], v[174:177], v[196:199], v[56:59]
	v_mfma_f32_16x16x32_bf16 v[48:51], v[188:191], v[196:199], v[48:51]
	v_mfma_f32_16x16x32_bf16 v[40:43], v[174:177], v[204:207], v[40:43]
	v_mfma_f32_16x16x32_bf16 v[32:35], v[188:191], v[204:207], v[32:35]
	v_mfma_f32_16x16x32_bf16 v[24:27], v[174:177], v[212:215], v[24:27]
	v_mfma_f32_16x16x32_bf16 v[16:19], v[188:191], v[212:215], v[16:19]
	v_mfma_f32_16x16x32_bf16 v[8:11], v[174:177], v[220:223], v[8:11]
	v_mfma_f32_16x16x32_bf16 v[0:3], v[188:191], v[220:223], v[0:3]
	s_barrier
	s_add_i32 s50, s50, 2
	s_add_u32 s20, s20, 0x100
	s_addc_u32 s21, s21, 0
	s_add_u32 s46, s46, 0x100
	s_addc_u32 s47, s47, 0
	s_cmp_gt_u32 s50, 13
	s_cbranch_scc0 .LBB0_705
	s_and_b64 vcc, exec, s[8:9]
	s_cbranch_vccz .LBB0_708
	s_barrier

.LBB0_787:
	ds_read_b128 v[144:147], v151
	ds_read_b128 v[156:159], v151 offset:1024
	ds_read_b128 v[160:163], v151 offset:2048
	ds_read_b128 v[164:167], v151 offset:3072
	ds_read_b128 v[168:171], v152
	ds_read_b128 v[172:175], v152 offset:1024
	ds_read_b128 v[176:179], v152 offset:2048
	ds_read_b128 v[184:187], v152 offset:3072
	s_add_u32 s20, s18, 0x100
	s_addc_u32 s21, s19, 0
	s_cmp_eq_u32 s47, 40
	s_cselect_b32 s25, s7, s21
	s_cselect_b32 s24, s6, s20
	s_cselect_b32 s23, s17, s46
	s_cselect_b32 s22, s16, s43
	v_lshl_add_u64 v[220:221], s[18:19], 0, v[136:137]
	s_add_i32 m0, s29, 0xc000
	ds_read_b128 v[188:191], v153
	ds_read_b128 v[192:195], v153 offset:1024
	ds_read_b128 v[196:199], v153 offset:2048
	ds_read_b128 v[200:203], v153 offset:3072
	ds_read_b128 v[204:207], v153 offset:4096
	ds_read_b128 v[208:211], v153 offset:5120
	ds_read_b128 v[212:215], v153 offset:6144
	ds_read_b128 v[216:219], v153 offset:7168
	global_load_lds_dwordx4 v[220:221], off
	v_lshl_add_u64 v[220:221], s[18:19], 0, v[138:139]
	s_add_i32 m0, s29, 0xe000
	s_nop 0
	global_load_lds_dwordx4 v[220:221], off
	s_waitcnt vmcnt(8)
	s_waitcnt lgkmcnt(0)
	s_barrier
	s_waitcnt lgkmcnt(0)
	v_mfma_f32_16x16x32_bf16 v[124:127], v[144:147], v[188:191], v[124:127]
	v_mfma_f32_16x16x32_bf16 v[120:123], v[160:163], v[188:191], v[120:123]
	v_mfma_f32_16x16x32_bf16 v[108:111], v[144:147], v[196:199], v[108:111]
	v_mfma_f32_16x16x32_bf16 v[104:107], v[160:163], v[196:199], v[104:107]
	v_mfma_f32_16x16x32_bf16 v[92:95], v[144:147], v[204:207], v[92:95]
	v_mfma_f32_16x16x32_bf16 v[88:91], v[160:163], v[204:207], v[88:91]
	v_mfma_f32_16x16x32_bf16 v[76:79], v[144:147], v[212:215], v[76:79]
	v_mfma_f32_16x16x32_bf16 v[72:75], v[160:163], v[212:215], v[72:75]
	v_mfma_f32_16x16x32_bf16 v[124:127], v[156:159], v[192:195], v[124:127]
	v_mfma_f32_16x16x32_bf16 v[120:123], v[164:167], v[192:195], v[120:123]
	v_mfma_f32_16x16x32_bf16 v[108:111], v[156:159], v[200:203], v[108:111]
	v_mfma_f32_16x16x32_bf16 v[104:107], v[164:167], v[200:203], v[104:107]
	v_mfma_f32_16x16x32_bf16 v[92:95], v[156:159], v[208:211], v[92:95]
	v_mfma_f32_16x16x32_bf16 v[88:91], v[164:167], v[208:211], v[88:91]
	v_mfma_f32_16x16x32_bf16 v[76:79], v[156:159], v[216:219], v[76:79]
	v_mfma_f32_16x16x32_bf16 v[72:75], v[164:167], v[216:219], v[72:75]
	v_mfma_f32_16x16x32_bf16 v[116:119], v[168:171], v[188:191], v[116:119]
	v_mfma_f32_16x16x32_bf16 v[112:115], v[176:179], v[188:191], v[112:115]
	v_mfma_f32_16x16x32_bf16 v[100:103], v[168:171], v[196:199], v[100:103]
	v_mfma_f32_16x16x32_bf16 v[96:99], v[176:179], v[196:199], v[96:99]
	v_mfma_f32_16x16x32_bf16 v[84:87], v[168:171], v[204:207], v[84:87]
	v_mfma_f32_16x16x32_bf16 v[80:83], v[176:179], v[204:207], v[80:83]
	v_mfma_f32_16x16x32_bf16 v[68:71], v[168:171], v[212:215], v[68:71]
	v_mfma_f32_16x16x32_bf16 v[64:67], v[176:179], v[212:215], v[64:67]
	v_mfma_f32_16x16x32_bf16 v[116:119], v[172:175], v[192:195], v[116:119]
	v_mfma_f32_16x16x32_bf16 v[112:115], v[184:187], v[192:195], v[112:115]
	v_mfma_f32_16x16x32_bf16 v[100:103], v[172:175], v[200:203], v[100:103]
	v_mfma_f32_16x16x32_bf16 v[96:99], v[184:187], v[200:203], v[96:99]
	v_mfma_f32_16x16x32_bf16 v[84:87], v[172:175], v[208:211], v[84:87]
	v_mfma_f32_16x16x32_bf16 v[80:83], v[184:187], v[208:211], v[80:83]
	v_mfma_f32_16x16x32_bf16 v[68:71], v[172:175], v[216:219], v[68:71]
	v_mfma_f32_16x16x32_bf16 v[64:67], v[184:187], v[216:219], v[64:67]
	s_barrier
	s_add_i32 s18, s37, s28
	v_lshl_add_u64 v[220:221], s[22:23], 0, v[130:131]
	s_mov_b32 m0, s18
	ds_read_b128 v[188:191], v153 offset:16384
	ds_read_b128 v[192:195], v153 offset:17408
	ds_read_b128 v[196:199], v153 offset:18432
	ds_read_b128 v[200:203], v153 offset:19456
	ds_read_b128 v[204:207], v153 offset:20480
	ds_read_b128 v[208:211], v153 offset:21504
	ds_read_b128 v[212:215], v153 offset:22528
	ds_read_b128 v[216:219], v153 offset:23552
	global_load_lds_dwordx4 v[220:221], off
	s_add_i32 m0, s18, 0x2000
	s_add_u32 s18, s22, 0xb0000
	v_lshl_add_u64 v[222:223], s[22:23], 0, v[134:135]
	s_addc_u32 s19, s23, 0
	s_add_i32 s50, s38, s28
	global_load_lds_dwordx4 v[222:223], off
	v_lshl_add_u64 v[224:225], s[18:19], 0, v[130:131]
	s_mov_b32 m0, s50
	v_lshl_add_u64 v[226:227], s[24:25], 0, v[132:133]
	global_load_lds_dwordx4 v[224:225], off
	v_lshl_add_u64 v[224:225], s[18:19], 0, v[134:135]
	s_add_i32 m0, s50, 0x2000
	s_nop 0
	global_load_lds_dwordx4 v[224:225], off
	v_lshl_add_u64 v[224:225], s[24:25], 0, v[128:129]
	s_mov_b32 m0, s29
	s_nop 0
	global_load_lds_dwordx4 v[224:225], off
	s_mov_b32 m0, s30
	s_nop 0
	global_load_lds_dwordx4 v[226:227], off
	s_waitcnt vmcnt(8)
	s_waitcnt lgkmcnt(0)
	s_barrier
	s_waitcnt lgkmcnt(0)
	v_mfma_f32_16x16x32_bf16 v[60:63], v[144:147], v[188:191], v[60:63]
	v_mfma_f32_16x16x32_bf16 v[56:59], v[160:163], v[188:191], v[56:59]
	v_mfma_f32_16x16x32_bf16 v[44:47], v[144:147], v[196:199], v[44:47]
	v_mfma_f32_16x16x32_bf16 v[40:43], v[160:163], v[196:199], v[40:43]
	v_mfma_f32_16x16x32_bf16 v[28:31], v[144:147], v[204:207], v[28:31]
	v_mfma_f32_16x16x32_bf16 v[24:27], v[160:163], v[204:207], v[24:27]
	v_mfma_f32_16x16x32_bf16 v[12:15], v[144:147], v[212:215], v[12:15]
	v_mfma_f32_16x16x32_bf16 v[8:11], v[160:163], v[212:215], v[8:11]
	v_mfma_f32_16x16x32_bf16 v[60:63], v[156:159], v[192:195], v[60:63]
	v_mfma_f32_16x16x32_bf16 v[56:59], v[164:167], v[192:195], v[56:59]
	v_mfma_f32_16x16x32_bf16 v[44:47], v[156:159], v[200:203], v[44:47]
	v_mfma_f32_16x16x32_bf16 v[40:43], v[164:167], v[200:203], v[40:43]
	v_mfma_f32_16x16x32_bf16 v[28:31], v[156:159], v[208:211], v[28:31]
	v_mfma_f32_16x16x32_bf16 v[24:27], v[164:167], v[208:211], v[24:27]
	v_mfma_f32_16x16x32_bf16 v[12:15], v[156:159], v[216:219], v[12:15]
	v_mfma_f32_16x16x32_bf16 v[8:11], v[164:167], v[216:219], v[8:11]
	v_mfma_f32_16x16x32_bf16 v[52:55], v[168:171], v[188:191], v[52:55]
	v_mfma_f32_16x16x32_bf16 v[48:51], v[176:179], v[188:191], v[48:51]
	v_mfma_f32_16x16x32_bf16 v[36:39], v[168:171], v[196:199], v[36:39]
	v_mfma_f32_16x16x32_bf16 v[32:35], v[176:179], v[196:199], v[32:35]
	v_mfma_f32_16x16x32_bf16 v[20:23], v[168:171], v[204:207], v[20:23]
	v_mfma_f32_16x16x32_bf16 v[16:19], v[176:179], v[204:207], v[16:19]
	v_mfma_f32_16x16x32_bf16 v[4:7], v[168:171], v[212:215], v[4:7]
	v_mfma_f32_16x16x32_bf16 v[0:3], v[176:179], v[212:215], v[0:3]
	v_mfma_f32_16x16x32_bf16 v[52:55], v[172:175], v[192:195], v[52:55]
	v_mfma_f32_16x16x32_bf16 v[48:51], v[184:187], v[192:195], v[48:51]
	v_mfma_f32_16x16x32_bf16 v[36:39], v[172:175], v[200:203], v[36:39]
	v_mfma_f32_16x16x32_bf16 v[32:35], v[184:187], v[200:203], v[32:35]
	v_mfma_f32_16x16x32_bf16 v[20:23], v[172:175], v[208:211], v[20:23]
	v_mfma_f32_16x16x32_bf16 v[16:19], v[184:187], v[208:211], v[16:19]
	v_mfma_f32_16x16x32_bf16 v[4:7], v[172:175], v[216:219], v[4:7]
	v_mfma_f32_16x16x32_bf16 v[0:3], v[184:187], v[216:219], v[0:3]
	s_barrier
	s_add_i32 s50, 0, 0x18000
	v_add_u32_e32 v155, s50, v149
	s_add_i32 s51, 0, 0x1c000
	ds_read_b128 v[144:147], v155
	ds_read_b128 v[156:159], v155 offset:1024
	ds_read_b128 v[160:163], v155 offset:2048
	ds_read_b128 v[164:167], v155 offset:3072
	v_add_u32_e32 v155, s51, v149
	ds_read_b128 v[168:171], v155
	ds_read_b128 v[172:175], v155 offset:1024
	ds_read_b128 v[176:179], v155 offset:2048
	ds_read_b128 v[184:187], v155 offset:3072
	s_add_u32 s18, s24, 0xb0000
	s_addc_u32 s19, s25, 0
	s_mov_b32 m0, s31
	v_lshl_add_u64 v[228:229], s[18:19], 0, v[128:129]
	ds_read_b128 v[188:191], v153 offset:32768
	ds_read_b128 v[192:195], v153 offset:33792
	ds_read_b128 v[196:199], v153 offset:34816
	ds_read_b128 v[200:203], v153 offset:35840
	ds_read_b128 v[204:207], v153 offset:36864
	ds_read_b128 v[208:211], v153 offset:37888
	ds_read_b128 v[212:215], v153 offset:38912
	ds_read_b128 v[216:219], v153 offset:39936
	global_load_lds_dwordx4 v[228:229], off
	v_lshl_add_u64 v[228:229], s[18:19], 0, v[132:133]
	s_mov_b32 m0, s33
	s_nop 0
	global_load_lds_dwordx4 v[228:229], off
	s_waitcnt vmcnt(8)
	s_waitcnt lgkmcnt(0)
	s_barrier
	s_waitcnt lgkmcnt(0)
	v_mfma_f32_16x16x32_bf16 v[124:127], v[144:147], v[188:191], v[124:127]
	v_mfma_f32_16x16x32_bf16 v[120:123], v[160:163], v[188:191], v[120:123]
	v_mfma_f32_16x16x32_bf16 v[108:111], v[144:147], v[196:199], v[108:111]
	v_mfma_f32_16x16x32_bf16 v[104:107], v[160:163], v[196:199], v[104:107]
	v_mfma_f32_16x16x32_bf16 v[92:95], v[144:147], v[204:207], v[92:95]
	v_mfma_f32_16x16x32_bf16 v[88:91], v[160:163], v[204:207], v[88:91]
	v_mfma_f32_16x16x32_bf16 v[76:79], v[144:147], v[212:215], v[76:79]
	v_mfma_f32_16x16x32_bf16 v[72:75], v[160:163], v[212:215], v[72:75]
	v_mfma_f32_16x16x32_bf16 v[124:127], v[156:159], v[192:195], v[124:127]
	v_mfma_f32_16x16x32_bf16 v[120:123], v[164:167], v[192:195], v[120:123]
	v_mfma_f32_16x16x32_bf16 v[108:111], v[156:159], v[200:203], v[108:111]
	v_mfma_f32_16x16x32_bf16 v[104:107], v[164:167], v[200:203], v[104:107]
	v_mfma_f32_16x16x32_bf16 v[92:95], v[156:159], v[208:211], v[92:95]
	v_mfma_f32_16x16x32_bf16 v[88:91], v[164:167], v[208:211], v[88:91]
	v_mfma_f32_16x16x32_bf16 v[76:79], v[156:159], v[216:219], v[76:79]
	v_mfma_f32_16x16x32_bf16 v[72:75], v[164:167], v[216:219], v[72:75]
	v_mfma_f32_16x16x32_bf16 v[116:119], v[168:171], v[188:191], v[116:119]
	v_mfma_f32_16x16x32_bf16 v[112:115], v[176:179], v[188:191], v[112:115]
	v_mfma_f32_16x16x32_bf16 v[100:103], v[168:171], v[196:199], v[100:103]
	v_mfma_f32_16x16x32_bf16 v[96:99], v[176:179], v[196:199], v[96:99]
	v_mfma_f32_16x16x32_bf16 v[84:87], v[168:171], v[204:207], v[84:87]
	v_mfma_f32_16x16x32_bf16 v[80:83], v[176:179], v[204:207], v[80:83]
	v_mfma_f32_16x16x32_bf16 v[68:71], v[168:171], v[212:215], v[68:71]
	v_mfma_f32_16x16x32_bf16 v[64:67], v[176:179], v[212:215], v[64:67]
	v_mfma_f32_16x16x32_bf16 v[116:119], v[172:175], v[192:195], v[116:119]
	v_mfma_f32_16x16x32_bf16 v[112:115], v[184:187], v[192:195], v[112:115]
	v_mfma_f32_16x16x32_bf16 v[100:103], v[172:175], v[200:203], v[100:103]
	v_mfma_f32_16x16x32_bf16 v[96:99], v[184:187], v[200:203], v[96:99]
	v_mfma_f32_16x16x32_bf16 v[84:87], v[172:175], v[208:211], v[84:87]
	v_mfma_f32_16x16x32_bf16 v[80:83], v[184:187], v[208:211], v[80:83]
	v_mfma_f32_16x16x32_bf16 v[68:71], v[172:175], v[216:219], v[68:71]
	v_mfma_f32_16x16x32_bf16 v[64:67], v[184:187], v[216:219], v[64:67]
	s_barrier
	s_add_i32 s18, s50, s28
	v_lshl_add_u64 v[220:221], v[220:221], 0, s[12:13]
	s_mov_b32 m0, s18
	ds_read_b128 v[188:191], v153 offset:49152
	ds_read_b128 v[192:195], v153 offset:50176
	ds_read_b128 v[196:199], v153 offset:51200
	ds_read_b128 v[200:203], v153 offset:52224
	ds_read_b128 v[204:207], v153 offset:53248
	ds_read_b128 v[208:211], v153 offset:54272
	ds_read_b128 v[212:215], v153 offset:55296
	ds_read_b128 v[216:219], v153 offset:56320
	global_load_lds_dwordx4 v[220:221], off
	s_add_i32 m0, s18, 0x2000
	s_add_u32 s18, s22, 0xb0080
	v_lshl_add_u64 v[220:221], v[222:223], 0, s[12:13]
	s_addc_u32 s19, s23, 0
	s_add_i32 s22, s51, s28
	global_load_lds_dwordx4 v[220:221], off
	v_lshl_add_u64 v[220:221], s[18:19], 0, v[130:131]
	s_mov_b32 m0, s22
	s_nop 0
	global_load_lds_dwordx4 v[220:221], off
	v_lshl_add_u64 v[220:221], s[18:19], 0, v[134:135]
	s_add_i32 m0, s22, 0x2000
	s_nop 0
	global_load_lds_dwordx4 v[220:221], off
	v_lshl_add_u64 v[220:221], v[224:225], 0, s[12:13]
	s_mov_b32 m0, s35
	s_nop 0
	global_load_lds_dwordx4 v[220:221], off
	v_lshl_add_u64 v[220:221], v[226:227], 0, s[12:13]
	s_mov_b32 m0, s36
	s_nop 0
	global_load_lds_dwordx4 v[220:221], off
	s_waitcnt vmcnt(8)
	s_waitcnt lgkmcnt(0)
	s_barrier
	s_waitcnt lgkmcnt(0)
	v_mfma_f32_16x16x32_bf16 v[60:63], v[144:147], v[188:191], v[60:63]
	v_mfma_f32_16x16x32_bf16 v[56:59], v[160:163], v[188:191], v[56:59]
	v_mfma_f32_16x16x32_bf16 v[44:47], v[144:147], v[196:199], v[44:47]
	v_mfma_f32_16x16x32_bf16 v[40:43], v[160:163], v[196:199], v[40:43]
	v_mfma_f32_16x16x32_bf16 v[28:31], v[144:147], v[204:207], v[28:31]
	v_mfma_f32_16x16x32_bf16 v[24:27], v[160:163], v[204:207], v[24:27]
	v_mfma_f32_16x16x32_bf16 v[12:15], v[144:147], v[212:215], v[12:15]
	v_mfma_f32_16x16x32_bf16 v[8:11], v[160:163], v[212:215], v[8:11]
	v_mfma_f32_16x16x32_bf16 v[60:63], v[156:159], v[192:195], v[60:63]
	v_mfma_f32_16x16x32_bf16 v[56:59], v[164:167], v[192:195], v[56:59]
	v_mfma_f32_16x16x32_bf16 v[44:47], v[156:159], v[200:203], v[44:47]
	v_mfma_f32_16x16x32_bf16 v[40:43], v[164:167], v[200:203], v[40:43]
	v_mfma_f32_16x16x32_bf16 v[28:31], v[156:159], v[208:211], v[28:31]
	v_mfma_f32_16x16x32_bf16 v[24:27], v[164:167], v[208:211], v[24:27]
	v_mfma_f32_16x16x32_bf16 v[12:15], v[156:159], v[216:219], v[12:15]
	v_mfma_f32_16x16x32_bf16 v[8:11], v[164:167], v[216:219], v[8:11]
	v_mfma_f32_16x16x32_bf16 v[52:55], v[168:171], v[188:191], v[52:55]
	v_mfma_f32_16x16x32_bf16 v[48:51], v[176:179], v[188:191], v[48:51]
	v_mfma_f32_16x16x32_bf16 v[36:39], v[168:171], v[196:199], v[36:39]
	v_mfma_f32_16x16x32_bf16 v[32:35], v[176:179], v[196:199], v[32:35]
	v_mfma_f32_16x16x32_bf16 v[20:23], v[168:171], v[204:207], v[20:23]
	v_mfma_f32_16x16x32_bf16 v[16:19], v[176:179], v[204:207], v[16:19]
	v_mfma_f32_16x16x32_bf16 v[4:7], v[168:171], v[212:215], v[4:7]
	v_mfma_f32_16x16x32_bf16 v[0:3], v[176:179], v[212:215], v[0:3]
	v_mfma_f32_16x16x32_bf16 v[52:55], v[172:175], v[192:195], v[52:55]
	v_mfma_f32_16x16x32_bf16 v[48:51], v[184:187], v[192:195], v[48:51]
	v_mfma_f32_16x16x32_bf16 v[36:39], v[172:175], v[200:203], v[36:39]
	v_mfma_f32_16x16x32_bf16 v[32:35], v[184:187], v[200:203], v[32:35]
	v_mfma_f32_16x16x32_bf16 v[20:23], v[172:175], v[208:211], v[20:23]
	v_mfma_f32_16x16x32_bf16 v[16:19], v[184:187], v[208:211], v[16:19]
	v_mfma_f32_16x16x32_bf16 v[4:7], v[172:175], v[216:219], v[4:7]
	v_mfma_f32_16x16x32_bf16 v[0:3], v[184:187], v[216:219], v[0:3]
	s_barrier
	s_add_i32 s47, s47, 2
	s_add_u32 s43, s43, 0x100
	s_addc_u32 s46, s46, 0
	s_cmp_gt_u32 s47, 41
	s_mov_b64 s[18:19], s[20:21]
	s_cbranch_scc0 .LBB0_787
	s_and_b64 vcc, exec, s[14:15]
	s_cbranch_vccz .LBB0_790
	s_barrier

.LBB0_877:
	ds_read_b128 v[144:147], v173
	ds_read_b128 v[148:151], v173 offset:1024
	ds_read_b128 v[152:155], v173 offset:2048
	ds_read_b128 v[156:159], v173 offset:3072
	ds_read_b128 v[184:187], v174
	ds_read_b128 v[188:191], v174 offset:1024
	ds_read_b128 v[192:195], v174 offset:2048
	ds_read_b128 v[196:199], v174 offset:3072
	s_add_u32 s30, s28, 0xfffc0080
	s_addc_u32 s31, s29, -1
	s_cmp_eq_u32 s56, 12
	s_cselect_b32 s35, s11, s31
	s_cselect_b32 s34, s23, s30
	s_cselect_b32 s31, s21, s55
	s_cselect_b32 s30, s53, s54
	v_lshl_add_u64 v[160:161], s[28:29], 0, v[136:137]
	s_add_i32 m0, s38, 0xc000
	ds_read_b128 v[200:203], v175
	ds_read_b128 v[204:207], v175 offset:1024
	ds_read_b128 v[208:211], v175 offset:2048
	ds_read_b128 v[212:215], v175 offset:3072
	ds_read_b128 v[216:219], v175 offset:4096
	ds_read_b128 v[220:223], v175 offset:5120
	ds_read_b128 v[224:227], v175 offset:6144
	ds_read_b128 v[228:231], v175 offset:7168
	global_load_lds_dwordx4 v[160:161], off
	v_lshl_add_u64 v[160:161], s[28:29], 0, v[138:139]
	s_add_i32 m0, s38, 0xe000
	s_nop 0
	global_load_lds_dwordx4 v[160:161], off
	s_waitcnt vmcnt(8)
	s_waitcnt lgkmcnt(0)
	s_barrier
	s_waitcnt lgkmcnt(0)
	v_mfma_f32_16x16x32_bf16 v[124:127], v[144:147], v[200:203], v[124:127]
	v_mfma_f32_16x16x32_bf16 v[120:123], v[152:155], v[200:203], v[120:123]
	v_mfma_f32_16x16x32_bf16 v[108:111], v[144:147], v[208:211], v[108:111]
	v_mfma_f32_16x16x32_bf16 v[104:107], v[152:155], v[208:211], v[104:107]
	v_mfma_f32_16x16x32_bf16 v[92:95], v[144:147], v[216:219], v[92:95]
	v_mfma_f32_16x16x32_bf16 v[88:91], v[152:155], v[216:219], v[88:91]
	v_mfma_f32_16x16x32_bf16 v[76:79], v[144:147], v[224:227], v[76:79]
	v_mfma_f32_16x16x32_bf16 v[72:75], v[152:155], v[224:227], v[72:75]
	v_mfma_f32_16x16x32_bf16 v[124:127], v[148:151], v[204:207], v[124:127]
	v_mfma_f32_16x16x32_bf16 v[120:123], v[156:159], v[204:207], v[120:123]
	v_mfma_f32_16x16x32_bf16 v[108:111], v[148:151], v[212:215], v[108:111]
	v_mfma_f32_16x16x32_bf16 v[104:107], v[156:159], v[212:215], v[104:107]
	v_mfma_f32_16x16x32_bf16 v[92:95], v[148:151], v[220:223], v[92:95]
	v_mfma_f32_16x16x32_bf16 v[88:91], v[156:159], v[220:223], v[88:91]
	v_mfma_f32_16x16x32_bf16 v[76:79], v[148:151], v[228:231], v[76:79]
	v_mfma_f32_16x16x32_bf16 v[72:75], v[156:159], v[228:231], v[72:75]
	v_mfma_f32_16x16x32_bf16 v[116:119], v[184:187], v[200:203], v[116:119]
	v_mfma_f32_16x16x32_bf16 v[112:115], v[192:195], v[200:203], v[112:115]
	v_mfma_f32_16x16x32_bf16 v[100:103], v[184:187], v[208:211], v[100:103]
	v_mfma_f32_16x16x32_bf16 v[96:99], v[192:195], v[208:211], v[96:99]
	v_mfma_f32_16x16x32_bf16 v[84:87], v[184:187], v[216:219], v[84:87]
	v_mfma_f32_16x16x32_bf16 v[80:83], v[192:195], v[216:219], v[80:83]
	v_mfma_f32_16x16x32_bf16 v[68:71], v[184:187], v[224:227], v[68:71]
	v_mfma_f32_16x16x32_bf16 v[64:67], v[192:195], v[224:227], v[64:67]
	v_mfma_f32_16x16x32_bf16 v[116:119], v[188:191], v[204:207], v[116:119]
	v_mfma_f32_16x16x32_bf16 v[112:115], v[196:199], v[204:207], v[112:115]
	v_mfma_f32_16x16x32_bf16 v[100:103], v[188:191], v[212:215], v[100:103]
	v_mfma_f32_16x16x32_bf16 v[96:99], v[196:199], v[212:215], v[96:99]
	v_mfma_f32_16x16x32_bf16 v[84:87], v[188:191], v[220:223], v[84:87]
	v_mfma_f32_16x16x32_bf16 v[80:83], v[196:199], v[220:223], v[80:83]
	v_mfma_f32_16x16x32_bf16 v[68:71], v[188:191], v[228:231], v[68:71]
	v_mfma_f32_16x16x32_bf16 v[64:67], v[196:199], v[228:231], v[64:67]
	s_barrier
	s_add_i32 s57, s47, s37
	v_lshl_add_u64 v[160:161], s[30:31], 0, v[130:131]
	s_mov_b32 m0, s57
	ds_read_b128 v[200:203], v175 offset:16384
	ds_read_b128 v[204:207], v175 offset:17408
	ds_read_b128 v[208:211], v175 offset:18432
	ds_read_b128 v[212:215], v175 offset:19456
	ds_read_b128 v[216:219], v175 offset:20480
	ds_read_b128 v[220:223], v175 offset:21504
	ds_read_b128 v[224:227], v175 offset:22528
	ds_read_b128 v[228:231], v175 offset:23552
	global_load_lds_dwordx4 v[160:161], off
	s_add_i32 m0, s57, 0x2000
	s_add_u32 s58, s30, 0x40000
	v_lshl_add_u64 v[178:179], s[30:31], 0, v[134:135]
	s_addc_u32 s59, s31, 0
	s_add_i32 s57, s50, s37
	global_load_lds_dwordx4 v[178:179], off
	v_lshl_add_u64 v[232:233], s[58:59], 0, v[130:131]
	s_mov_b32 m0, s57
	v_lshl_add_u64 v[234:235], s[34:35], 0, v[132:133]
	global_load_lds_dwordx4 v[232:233], off
	v_lshl_add_u64 v[232:233], s[58:59], 0, v[134:135]
	s_add_i32 m0, s57, 0x2000
	s_nop 0
	global_load_lds_dwordx4 v[232:233], off
	v_lshl_add_u64 v[232:233], s[34:35], 0, v[128:129]
	s_mov_b32 m0, s38
	s_nop 0
	global_load_lds_dwordx4 v[232:233], off
	s_mov_b32 m0, s39
	s_nop 0
	global_load_lds_dwordx4 v[234:235], off
	s_waitcnt vmcnt(8)
	s_waitcnt lgkmcnt(0)
	s_barrier
	s_waitcnt lgkmcnt(0)
	v_mfma_f32_16x16x32_bf16 v[60:63], v[144:147], v[200:203], v[60:63]
	v_mfma_f32_16x16x32_bf16 v[56:59], v[152:155], v[200:203], v[56:59]
	v_mfma_f32_16x16x32_bf16 v[44:47], v[144:147], v[208:211], v[44:47]
	v_mfma_f32_16x16x32_bf16 v[40:43], v[152:155], v[208:211], v[40:43]
	v_mfma_f32_16x16x32_bf16 v[28:31], v[144:147], v[216:219], v[28:31]
	v_mfma_f32_16x16x32_bf16 v[24:27], v[152:155], v[216:219], v[24:27]
	v_mfma_f32_16x16x32_bf16 v[12:15], v[144:147], v[224:227], v[12:15]
	v_mfma_f32_16x16x32_bf16 v[8:11], v[152:155], v[224:227], v[8:11]
	v_mfma_f32_16x16x32_bf16 v[60:63], v[148:151], v[204:207], v[60:63]
	v_mfma_f32_16x16x32_bf16 v[56:59], v[156:159], v[204:207], v[56:59]
	v_mfma_f32_16x16x32_bf16 v[44:47], v[148:151], v[212:215], v[44:47]
	v_mfma_f32_16x16x32_bf16 v[40:43], v[156:159], v[212:215], v[40:43]
	v_mfma_f32_16x16x32_bf16 v[28:31], v[148:151], v[220:223], v[28:31]
	v_mfma_f32_16x16x32_bf16 v[24:27], v[156:159], v[220:223], v[24:27]
	v_mfma_f32_16x16x32_bf16 v[12:15], v[148:151], v[228:231], v[12:15]
	v_mfma_f32_16x16x32_bf16 v[8:11], v[156:159], v[228:231], v[8:11]
	v_mfma_f32_16x16x32_bf16 v[52:55], v[184:187], v[200:203], v[52:55]
	v_mfma_f32_16x16x32_bf16 v[48:51], v[192:195], v[200:203], v[48:51]
	v_mfma_f32_16x16x32_bf16 v[36:39], v[184:187], v[208:211], v[36:39]
	v_mfma_f32_16x16x32_bf16 v[32:35], v[192:195], v[208:211], v[32:35]
	v_mfma_f32_16x16x32_bf16 v[20:23], v[184:187], v[216:219], v[20:23]
	v_mfma_f32_16x16x32_bf16 v[16:19], v[192:195], v[216:219], v[16:19]
	v_mfma_f32_16x16x32_bf16 v[4:7], v[184:187], v[224:227], v[4:7]
	v_mfma_f32_16x16x32_bf16 v[0:3], v[192:195], v[224:227], v[0:3]
	v_mfma_f32_16x16x32_bf16 v[52:55], v[188:191], v[204:207], v[52:55]
	v_mfma_f32_16x16x32_bf16 v[48:51], v[196:199], v[204:207], v[48:51]
	v_mfma_f32_16x16x32_bf16 v[36:39], v[188:191], v[212:215], v[36:39]
	v_mfma_f32_16x16x32_bf16 v[32:35], v[196:199], v[212:215], v[32:35]
	v_mfma_f32_16x16x32_bf16 v[20:23], v[188:191], v[220:223], v[20:23]
	v_mfma_f32_16x16x32_bf16 v[16:19], v[196:199], v[220:223], v[16:19]
	v_mfma_f32_16x16x32_bf16 v[4:7], v[188:191], v[228:231], v[4:7]
	v_mfma_f32_16x16x32_bf16 v[0:3], v[196:199], v[228:231], v[0:3]
	s_barrier
	s_add_i32 s57, 0, 0x18000
	s_add_i32 s58, 0, 0x1c000
	v_add_u32_e32 v156, s57, v163
	v_add_u32_e32 v177, s58, v163
	ds_read_b128 v[144:147], v156
	ds_read_b128 v[148:151], v156 offset:1024
	ds_read_b128 v[152:155], v156 offset:2048
	ds_read_b128 v[156:159], v156 offset:3072
	ds_read_b128 v[184:187], v177
	ds_read_b128 v[188:191], v177 offset:1024
	ds_read_b128 v[192:195], v177 offset:2048
	ds_read_b128 v[196:199], v177 offset:3072
	s_add_u32 s34, s34, 0x40000
	s_addc_u32 s35, s35, 0
	s_mov_b32 m0, s40
	v_lshl_add_u64 v[236:237], s[34:35], 0, v[128:129]
	ds_read_b128 v[200:203], v175 offset:32768
	ds_read_b128 v[204:207], v175 offset:33792
	ds_read_b128 v[208:211], v175 offset:34816
	ds_read_b128 v[212:215], v175 offset:35840
	ds_read_b128 v[216:219], v175 offset:36864
	ds_read_b128 v[220:223], v175 offset:37888
	ds_read_b128 v[224:227], v175 offset:38912
	ds_read_b128 v[228:231], v175 offset:39936
	global_load_lds_dwordx4 v[236:237], off
	v_lshl_add_u64 v[236:237], s[34:35], 0, v[132:133]
	s_mov_b32 m0, s41
	s_nop 0
	global_load_lds_dwordx4 v[236:237], off
	s_waitcnt vmcnt(8)
	s_waitcnt lgkmcnt(0)
	s_barrier
	s_waitcnt lgkmcnt(0)
	v_mfma_f32_16x16x32_bf16 v[124:127], v[144:147], v[200:203], v[124:127]
	v_mfma_f32_16x16x32_bf16 v[120:123], v[152:155], v[200:203], v[120:123]
	v_mfma_f32_16x16x32_bf16 v[108:111], v[144:147], v[208:211], v[108:111]
	v_mfma_f32_16x16x32_bf16 v[104:107], v[152:155], v[208:211], v[104:107]
	v_mfma_f32_16x16x32_bf16 v[92:95], v[144:147], v[216:219], v[92:95]
	v_mfma_f32_16x16x32_bf16 v[88:91], v[152:155], v[216:219], v[88:91]
	v_mfma_f32_16x16x32_bf16 v[76:79], v[144:147], v[224:227], v[76:79]
	v_mfma_f32_16x16x32_bf16 v[72:75], v[152:155], v[224:227], v[72:75]
	v_mfma_f32_16x16x32_bf16 v[124:127], v[148:151], v[204:207], v[124:127]
	v_mfma_f32_16x16x32_bf16 v[120:123], v[156:159], v[204:207], v[120:123]
	v_mfma_f32_16x16x32_bf16 v[108:111], v[148:151], v[212:215], v[108:111]
	v_mfma_f32_16x16x32_bf16 v[104:107], v[156:159], v[212:215], v[104:107]
	v_mfma_f32_16x16x32_bf16 v[92:95], v[148:151], v[220:223], v[92:95]
	v_mfma_f32_16x16x32_bf16 v[88:91], v[156:159], v[220:223], v[88:91]
	v_mfma_f32_16x16x32_bf16 v[76:79], v[148:151], v[228:231], v[76:79]
	v_mfma_f32_16x16x32_bf16 v[72:75], v[156:159], v[228:231], v[72:75]
	v_mfma_f32_16x16x32_bf16 v[116:119], v[184:187], v[200:203], v[116:119]
	v_mfma_f32_16x16x32_bf16 v[112:115], v[192:195], v[200:203], v[112:115]
	v_mfma_f32_16x16x32_bf16 v[100:103], v[184:187], v[208:211], v[100:103]
	v_mfma_f32_16x16x32_bf16 v[96:99], v[192:195], v[208:211], v[96:99]
	v_mfma_f32_16x16x32_bf16 v[84:87], v[184:187], v[216:219], v[84:87]
	v_mfma_f32_16x16x32_bf16 v[80:83], v[192:195], v[216:219], v[80:83]
	v_mfma_f32_16x16x32_bf16 v[68:71], v[184:187], v[224:227], v[68:71]
	v_mfma_f32_16x16x32_bf16 v[64:67], v[192:195], v[224:227], v[64:67]
	v_mfma_f32_16x16x32_bf16 v[116:119], v[188:191], v[204:207], v[116:119]
	v_mfma_f32_16x16x32_bf16 v[112:115], v[196:199], v[204:207], v[112:115]
	v_mfma_f32_16x16x32_bf16 v[100:103], v[188:191], v[212:215], v[100:103]
	v_mfma_f32_16x16x32_bf16 v[96:99], v[196:199], v[212:215], v[96:99]
	v_mfma_f32_16x16x32_bf16 v[84:87], v[188:191], v[220:223], v[84:87]
	v_mfma_f32_16x16x32_bf16 v[80:83], v[196:199], v[220:223], v[80:83]
	v_mfma_f32_16x16x32_bf16 v[68:71], v[188:191], v[228:231], v[68:71]
	v_mfma_f32_16x16x32_bf16 v[64:67], v[196:199], v[228:231], v[64:67]
	s_barrier
	s_add_i32 s34, s57, s37
	v_lshl_add_u64 v[160:161], v[160:161], 0, s[14:15]
	s_mov_b32 m0, s34
	ds_read_b128 v[200:203], v175 offset:49152
	ds_read_b128 v[204:207], v175 offset:50176
	ds_read_b128 v[208:211], v175 offset:51200
	ds_read_b128 v[212:215], v175 offset:52224
	ds_read_b128 v[216:219], v175 offset:53248
	ds_read_b128 v[220:223], v175 offset:54272
	ds_read_b128 v[224:227], v175 offset:55296
	ds_read_b128 v[228:231], v175 offset:56320
	global_load_lds_dwordx4 v[160:161], off
	s_add_i32 m0, s34, 0x2000
	s_add_u32 s30, s30, 0x40080
	v_lshl_add_u64 v[160:161], v[178:179], 0, s[14:15]
	s_addc_u32 s31, s31, 0
	s_add_i32 s34, s58, s37
	global_load_lds_dwordx4 v[160:161], off
	v_lshl_add_u64 v[160:161], s[30:31], 0, v[130:131]
	s_mov_b32 m0, s34
	s_nop 0
	global_load_lds_dwordx4 v[160:161], off
	v_lshl_add_u64 v[160:161], s[30:31], 0, v[134:135]
	s_add_i32 m0, s34, 0x2000
	s_nop 0
	global_load_lds_dwordx4 v[160:161], off
	v_lshl_add_u64 v[160:161], v[232:233], 0, s[14:15]
	s_mov_b32 m0, s42
	s_nop 0
	global_load_lds_dwordx4 v[160:161], off
	v_lshl_add_u64 v[160:161], v[234:235], 0, s[14:15]
	s_mov_b32 m0, s43
	s_nop 0
	global_load_lds_dwordx4 v[160:161], off
	s_waitcnt vmcnt(8)
	s_waitcnt lgkmcnt(0)
	s_barrier
	s_waitcnt lgkmcnt(0)
	v_mfma_f32_16x16x32_bf16 v[60:63], v[144:147], v[200:203], v[60:63]
	v_mfma_f32_16x16x32_bf16 v[56:59], v[152:155], v[200:203], v[56:59]
	v_mfma_f32_16x16x32_bf16 v[44:47], v[144:147], v[208:211], v[44:47]
	v_mfma_f32_16x16x32_bf16 v[40:43], v[152:155], v[208:211], v[40:43]
	v_mfma_f32_16x16x32_bf16 v[28:31], v[144:147], v[216:219], v[28:31]
	v_mfma_f32_16x16x32_bf16 v[24:27], v[152:155], v[216:219], v[24:27]
	v_mfma_f32_16x16x32_bf16 v[12:15], v[144:147], v[224:227], v[12:15]
	v_mfma_f32_16x16x32_bf16 v[8:11], v[152:155], v[224:227], v[8:11]
	v_mfma_f32_16x16x32_bf16 v[60:63], v[148:151], v[204:207], v[60:63]
	v_mfma_f32_16x16x32_bf16 v[56:59], v[156:159], v[204:207], v[56:59]
	v_mfma_f32_16x16x32_bf16 v[44:47], v[148:151], v[212:215], v[44:47]
	v_mfma_f32_16x16x32_bf16 v[40:43], v[156:159], v[212:215], v[40:43]
	v_mfma_f32_16x16x32_bf16 v[28:31], v[148:151], v[220:223], v[28:31]
	v_mfma_f32_16x16x32_bf16 v[24:27], v[156:159], v[220:223], v[24:27]
	v_mfma_f32_16x16x32_bf16 v[12:15], v[148:151], v[228:231], v[12:15]
	v_mfma_f32_16x16x32_bf16 v[8:11], v[156:159], v[228:231], v[8:11]
	v_mfma_f32_16x16x32_bf16 v[52:55], v[184:187], v[200:203], v[52:55]
	v_mfma_f32_16x16x32_bf16 v[48:51], v[192:195], v[200:203], v[48:51]
	v_mfma_f32_16x16x32_bf16 v[36:39], v[184:187], v[208:211], v[36:39]
	v_mfma_f32_16x16x32_bf16 v[32:35], v[192:195], v[208:211], v[32:35]
	v_mfma_f32_16x16x32_bf16 v[20:23], v[184:187], v[216:219], v[20:23]
	v_mfma_f32_16x16x32_bf16 v[16:19], v[192:195], v[216:219], v[16:19]
	v_mfma_f32_16x16x32_bf16 v[4:7], v[184:187], v[224:227], v[4:7]
	v_mfma_f32_16x16x32_bf16 v[0:3], v[192:195], v[224:227], v[0:3]
	v_mfma_f32_16x16x32_bf16 v[52:55], v[188:191], v[204:207], v[52:55]
	v_mfma_f32_16x16x32_bf16 v[48:51], v[196:199], v[204:207], v[48:51]
	v_mfma_f32_16x16x32_bf16 v[36:39], v[188:191], v[212:215], v[36:39]
	v_mfma_f32_16x16x32_bf16 v[32:35], v[196:199], v[212:215], v[32:35]
	v_mfma_f32_16x16x32_bf16 v[20:23], v[188:191], v[220:223], v[20:23]
	v_mfma_f32_16x16x32_bf16 v[16:19], v[196:199], v[220:223], v[16:19]
	v_mfma_f32_16x16x32_bf16 v[4:7], v[188:191], v[228:231], v[4:7]
	v_mfma_f32_16x16x32_bf16 v[0:3], v[196:199], v[228:231], v[0:3]
	s_barrier
	s_add_i32 s56, s56, 2
	s_add_u32 s28, s28, 0x100
	s_addc_u32 s29, s29, 0
	s_add_u32 s54, s54, 0x100
	s_addc_u32 s55, s55, 0
	s_cmp_gt_u32 s56, 13
	s_cbranch_scc0 .LBB0_877
	s_and_b64 vcc, exec, s[16:17]
	s_cbranch_vccz .LBB0_880
	s_barrier

.LBB0_1291:
	ds_read_b128 v[144:147], v151
	ds_read_b128 v[156:159], v151 offset:1024
	ds_read_b128 v[160:163], v151 offset:2048
	ds_read_b128 v[164:167], v151 offset:3072
	ds_read_b128 v[168:171], v152
	ds_read_b128 v[172:175], v152 offset:1024
	ds_read_b128 v[176:179], v152 offset:2048
	ds_read_b128 v[184:187], v152 offset:3072
	s_add_u32 s26, s24, 0xfffc0080
	s_addc_u32 s27, s25, -1
	s_cmp_eq_u32 s47, 12
	s_cselect_b32 s29, s17, s27
	s_cselect_b32 s28, s23, s26
	s_cselect_b32 s27, s15, s46
	s_cselect_b32 s26, s44, s45
	v_lshl_add_u64 v[220:221], s[24:25], 0, v[136:137]
	s_add_i32 m0, s34, 0xc000
	ds_read_b128 v[188:191], v153
	ds_read_b128 v[192:195], v153 offset:1024
	ds_read_b128 v[196:199], v153 offset:2048
	ds_read_b128 v[200:203], v153 offset:3072
	ds_read_b128 v[204:207], v153 offset:4096
	ds_read_b128 v[208:211], v153 offset:5120
	ds_read_b128 v[212:215], v153 offset:6144
	ds_read_b128 v[216:219], v153 offset:7168
	global_load_lds_dwordx4 v[220:221], off
	v_lshl_add_u64 v[220:221], s[24:25], 0, v[138:139]
	s_add_i32 m0, s34, 0xe000
	s_nop 0
	global_load_lds_dwordx4 v[220:221], off
	s_waitcnt vmcnt(8)
	s_waitcnt lgkmcnt(0)
	s_barrier
	s_waitcnt lgkmcnt(0)
	v_mfma_f32_16x16x32_bf16 v[124:127], v[144:147], v[188:191], v[124:127]
	v_mfma_f32_16x16x32_bf16 v[120:123], v[160:163], v[188:191], v[120:123]
	v_mfma_f32_16x16x32_bf16 v[108:111], v[144:147], v[196:199], v[108:111]
	v_mfma_f32_16x16x32_bf16 v[104:107], v[160:163], v[196:199], v[104:107]
	v_mfma_f32_16x16x32_bf16 v[92:95], v[144:147], v[204:207], v[92:95]
	v_mfma_f32_16x16x32_bf16 v[88:91], v[160:163], v[204:207], v[88:91]
	v_mfma_f32_16x16x32_bf16 v[76:79], v[144:147], v[212:215], v[76:79]
	v_mfma_f32_16x16x32_bf16 v[72:75], v[160:163], v[212:215], v[72:75]
	v_mfma_f32_16x16x32_bf16 v[124:127], v[156:159], v[192:195], v[124:127]
	v_mfma_f32_16x16x32_bf16 v[120:123], v[164:167], v[192:195], v[120:123]
	v_mfma_f32_16x16x32_bf16 v[108:111], v[156:159], v[200:203], v[108:111]
	v_mfma_f32_16x16x32_bf16 v[104:107], v[164:167], v[200:203], v[104:107]
	v_mfma_f32_16x16x32_bf16 v[92:95], v[156:159], v[208:211], v[92:95]
	v_mfma_f32_16x16x32_bf16 v[88:91], v[164:167], v[208:211], v[88:91]
	v_mfma_f32_16x16x32_bf16 v[76:79], v[156:159], v[216:219], v[76:79]
	v_mfma_f32_16x16x32_bf16 v[72:75], v[164:167], v[216:219], v[72:75]
	v_mfma_f32_16x16x32_bf16 v[116:119], v[168:171], v[188:191], v[116:119]
	v_mfma_f32_16x16x32_bf16 v[112:115], v[176:179], v[188:191], v[112:115]
	v_mfma_f32_16x16x32_bf16 v[100:103], v[168:171], v[196:199], v[100:103]
	v_mfma_f32_16x16x32_bf16 v[96:99], v[176:179], v[196:199], v[96:99]
	v_mfma_f32_16x16x32_bf16 v[84:87], v[168:171], v[204:207], v[84:87]
	v_mfma_f32_16x16x32_bf16 v[80:83], v[176:179], v[204:207], v[80:83]
	v_mfma_f32_16x16x32_bf16 v[68:71], v[168:171], v[212:215], v[68:71]
	v_mfma_f32_16x16x32_bf16 v[64:67], v[176:179], v[212:215], v[64:67]
	v_mfma_f32_16x16x32_bf16 v[116:119], v[172:175], v[192:195], v[116:119]
	v_mfma_f32_16x16x32_bf16 v[112:115], v[184:187], v[192:195], v[112:115]
	v_mfma_f32_16x16x32_bf16 v[100:103], v[172:175], v[200:203], v[100:103]
	v_mfma_f32_16x16x32_bf16 v[96:99], v[184:187], v[200:203], v[96:99]
	v_mfma_f32_16x16x32_bf16 v[84:87], v[172:175], v[208:211], v[84:87]
	v_mfma_f32_16x16x32_bf16 v[80:83], v[184:187], v[208:211], v[80:83]
	v_mfma_f32_16x16x32_bf16 v[68:71], v[172:175], v[216:219], v[68:71]
	v_mfma_f32_16x16x32_bf16 v[64:67], v[184:187], v[216:219], v[64:67]
	s_barrier
	s_add_i32 s50, s41, s33
	v_lshl_add_u64 v[220:221], s[26:27], 0, v[130:131]
	s_mov_b32 m0, s50
	ds_read_b128 v[188:191], v153 offset:16384
	ds_read_b128 v[192:195], v153 offset:17408
	ds_read_b128 v[196:199], v153 offset:18432
	ds_read_b128 v[200:203], v153 offset:19456
	ds_read_b128 v[204:207], v153 offset:20480
	ds_read_b128 v[208:211], v153 offset:21504
	ds_read_b128 v[212:215], v153 offset:22528
	ds_read_b128 v[216:219], v153 offset:23552
	global_load_lds_dwordx4 v[220:221], off
	s_add_i32 m0, s50, 0x2000
	s_add_u32 s50, s26, 0x40000
	v_lshl_add_u64 v[222:223], s[26:27], 0, v[134:135]
	s_addc_u32 s51, s27, 0
	s_add_i32 s52, s42, s33
	global_load_lds_dwordx4 v[222:223], off
	v_lshl_add_u64 v[224:225], s[50:51], 0, v[130:131]
	s_mov_b32 m0, s52
	v_lshl_add_u64 v[226:227], s[28:29], 0, v[132:133]
	global_load_lds_dwordx4 v[224:225], off
	v_lshl_add_u64 v[224:225], s[50:51], 0, v[134:135]
	s_add_i32 m0, s52, 0x2000
	s_nop 0
	global_load_lds_dwordx4 v[224:225], off
	v_lshl_add_u64 v[224:225], s[28:29], 0, v[128:129]
	s_mov_b32 m0, s34
	s_nop 0
	global_load_lds_dwordx4 v[224:225], off
	s_mov_b32 m0, s35
	s_nop 0
	global_load_lds_dwordx4 v[226:227], off
	s_waitcnt vmcnt(8)
	s_waitcnt lgkmcnt(0)
	s_barrier
	s_waitcnt lgkmcnt(0)
	v_mfma_f32_16x16x32_bf16 v[60:63], v[144:147], v[188:191], v[60:63]
	v_mfma_f32_16x16x32_bf16 v[56:59], v[160:163], v[188:191], v[56:59]
	v_mfma_f32_16x16x32_bf16 v[44:47], v[144:147], v[196:199], v[44:47]
	v_mfma_f32_16x16x32_bf16 v[40:43], v[160:163], v[196:199], v[40:43]
	v_mfma_f32_16x16x32_bf16 v[28:31], v[144:147], v[204:207], v[28:31]
	v_mfma_f32_16x16x32_bf16 v[24:27], v[160:163], v[204:207], v[24:27]
	v_mfma_f32_16x16x32_bf16 v[12:15], v[144:147], v[212:215], v[12:15]
	v_mfma_f32_16x16x32_bf16 v[8:11], v[160:163], v[212:215], v[8:11]
	v_mfma_f32_16x16x32_bf16 v[60:63], v[156:159], v[192:195], v[60:63]
	v_mfma_f32_16x16x32_bf16 v[56:59], v[164:167], v[192:195], v[56:59]
	v_mfma_f32_16x16x32_bf16 v[44:47], v[156:159], v[200:203], v[44:47]
	v_mfma_f32_16x16x32_bf16 v[40:43], v[164:167], v[200:203], v[40:43]
	v_mfma_f32_16x16x32_bf16 v[28:31], v[156:159], v[208:211], v[28:31]
	v_mfma_f32_16x16x32_bf16 v[24:27], v[164:167], v[208:211], v[24:27]
	v_mfma_f32_16x16x32_bf16 v[12:15], v[156:159], v[216:219], v[12:15]
	v_mfma_f32_16x16x32_bf16 v[8:11], v[164:167], v[216:219], v[8:11]
	v_mfma_f32_16x16x32_bf16 v[52:55], v[168:171], v[188:191], v[52:55]
	v_mfma_f32_16x16x32_bf16 v[48:51], v[176:179], v[188:191], v[48:51]
	v_mfma_f32_16x16x32_bf16 v[36:39], v[168:171], v[196:199], v[36:39]
	v_mfma_f32_16x16x32_bf16 v[32:35], v[176:179], v[196:199], v[32:35]
	v_mfma_f32_16x16x32_bf16 v[20:23], v[168:171], v[204:207], v[20:23]
	v_mfma_f32_16x16x32_bf16 v[16:19], v[176:179], v[204:207], v[16:19]
	v_mfma_f32_16x16x32_bf16 v[4:7], v[168:171], v[212:215], v[4:7]
	v_mfma_f32_16x16x32_bf16 v[0:3], v[176:179], v[212:215], v[0:3]
	v_mfma_f32_16x16x32_bf16 v[52:55], v[172:175], v[192:195], v[52:55]
	v_mfma_f32_16x16x32_bf16 v[48:51], v[184:187], v[192:195], v[48:51]
	v_mfma_f32_16x16x32_bf16 v[36:39], v[172:175], v[200:203], v[36:39]
	v_mfma_f32_16x16x32_bf16 v[32:35], v[184:187], v[200:203], v[32:35]
	v_mfma_f32_16x16x32_bf16 v[20:23], v[172:175], v[208:211], v[20:23]
	v_mfma_f32_16x16x32_bf16 v[16:19], v[184:187], v[208:211], v[16:19]
	v_mfma_f32_16x16x32_bf16 v[4:7], v[172:175], v[216:219], v[4:7]
	v_mfma_f32_16x16x32_bf16 v[0:3], v[184:187], v[216:219], v[0:3]
	s_barrier
	s_add_i32 s50, 0, 0x18000
	v_add_u32_e32 v155, s50, v149
	s_add_i32 s51, 0, 0x1c000
	ds_read_b128 v[144:147], v155
	ds_read_b128 v[156:159], v155 offset:1024
	ds_read_b128 v[160:163], v155 offset:2048
	ds_read_b128 v[164:167], v155 offset:3072
	v_add_u32_e32 v155, s51, v149
	ds_read_b128 v[168:171], v155
	ds_read_b128 v[172:175], v155 offset:1024
	ds_read_b128 v[176:179], v155 offset:2048
	ds_read_b128 v[184:187], v155 offset:3072
	s_add_u32 s28, s28, 0x40000
	s_addc_u32 s29, s29, 0
	s_mov_b32 m0, s36
	v_lshl_add_u64 v[228:229], s[28:29], 0, v[128:129]
	ds_read_b128 v[188:191], v153 offset:32768
	ds_read_b128 v[192:195], v153 offset:33792
	ds_read_b128 v[196:199], v153 offset:34816
	ds_read_b128 v[200:203], v153 offset:35840
	ds_read_b128 v[204:207], v153 offset:36864
	ds_read_b128 v[208:211], v153 offset:37888
	ds_read_b128 v[212:215], v153 offset:38912
	ds_read_b128 v[216:219], v153 offset:39936
	global_load_lds_dwordx4 v[228:229], off
	v_lshl_add_u64 v[228:229], s[28:29], 0, v[132:133]
	s_mov_b32 m0, s37
	s_nop 0
	global_load_lds_dwordx4 v[228:229], off
	s_waitcnt vmcnt(8)
	s_waitcnt lgkmcnt(0)
	s_barrier
	s_waitcnt lgkmcnt(0)
	v_mfma_f32_16x16x32_bf16 v[124:127], v[144:147], v[188:191], v[124:127]
	v_mfma_f32_16x16x32_bf16 v[120:123], v[160:163], v[188:191], v[120:123]
	v_mfma_f32_16x16x32_bf16 v[108:111], v[144:147], v[196:199], v[108:111]
	v_mfma_f32_16x16x32_bf16 v[104:107], v[160:163], v[196:199], v[104:107]
	v_mfma_f32_16x16x32_bf16 v[92:95], v[144:147], v[204:207], v[92:95]
	v_mfma_f32_16x16x32_bf16 v[88:91], v[160:163], v[204:207], v[88:91]
	v_mfma_f32_16x16x32_bf16 v[76:79], v[144:147], v[212:215], v[76:79]
	v_mfma_f32_16x16x32_bf16 v[72:75], v[160:163], v[212:215], v[72:75]
	v_mfma_f32_16x16x32_bf16 v[124:127], v[156:159], v[192:195], v[124:127]
	v_mfma_f32_16x16x32_bf16 v[120:123], v[164:167], v[192:195], v[120:123]
	v_mfma_f32_16x16x32_bf16 v[108:111], v[156:159], v[200:203], v[108:111]
	v_mfma_f32_16x16x32_bf16 v[104:107], v[164:167], v[200:203], v[104:107]
	v_mfma_f32_16x16x32_bf16 v[92:95], v[156:159], v[208:211], v[92:95]
	v_mfma_f32_16x16x32_bf16 v[88:91], v[164:167], v[208:211], v[88:91]
	v_mfma_f32_16x16x32_bf16 v[76:79], v[156:159], v[216:219], v[76:79]
	v_mfma_f32_16x16x32_bf16 v[72:75], v[164:167], v[216:219], v[72:75]
	v_mfma_f32_16x16x32_bf16 v[116:119], v[168:171], v[188:191], v[116:119]
	v_mfma_f32_16x16x32_bf16 v[112:115], v[176:179], v[188:191], v[112:115]
	v_mfma_f32_16x16x32_bf16 v[100:103], v[168:171], v[196:199], v[100:103]
	v_mfma_f32_16x16x32_bf16 v[96:99], v[176:179], v[196:199], v[96:99]
	v_mfma_f32_16x16x32_bf16 v[84:87], v[168:171], v[204:207], v[84:87]
	v_mfma_f32_16x16x32_bf16 v[80:83], v[176:179], v[204:207], v[80:83]
	v_mfma_f32_16x16x32_bf16 v[68:71], v[168:171], v[212:215], v[68:71]
	v_mfma_f32_16x16x32_bf16 v[64:67], v[176:179], v[212:215], v[64:67]
	v_mfma_f32_16x16x32_bf16 v[116:119], v[172:175], v[192:195], v[116:119]
	v_mfma_f32_16x16x32_bf16 v[112:115], v[184:187], v[192:195], v[112:115]
	v_mfma_f32_16x16x32_bf16 v[100:103], v[172:175], v[200:203], v[100:103]
	v_mfma_f32_16x16x32_bf16 v[96:99], v[184:187], v[200:203], v[96:99]
	v_mfma_f32_16x16x32_bf16 v[84:87], v[172:175], v[208:211], v[84:87]
	v_mfma_f32_16x16x32_bf16 v[80:83], v[184:187], v[208:211], v[80:83]
	v_mfma_f32_16x16x32_bf16 v[68:71], v[172:175], v[216:219], v[68:71]
	v_mfma_f32_16x16x32_bf16 v[64:67], v[184:187], v[216:219], v[64:67]
	s_barrier
	s_add_i32 s28, s50, s33
	v_lshl_add_u64 v[220:221], v[220:221], 0, s[10:11]
	s_mov_b32 m0, s28
	ds_read_b128 v[188:191], v153 offset:49152
	ds_read_b128 v[192:195], v153 offset:50176
	ds_read_b128 v[196:199], v153 offset:51200
	ds_read_b128 v[200:203], v153 offset:52224
	ds_read_b128 v[204:207], v153 offset:53248
	ds_read_b128 v[208:211], v153 offset:54272
	ds_read_b128 v[212:215], v153 offset:55296
	ds_read_b128 v[216:219], v153 offset:56320
	global_load_lds_dwordx4 v[220:221], off
	s_add_i32 m0, s28, 0x2000
	s_add_u32 s26, s26, 0x40080
	v_lshl_add_u64 v[220:221], v[222:223], 0, s[10:11]
	s_addc_u32 s27, s27, 0
	s_add_i32 s28, s51, s33
	global_load_lds_dwordx4 v[220:221], off
	v_lshl_add_u64 v[220:221], s[26:27], 0, v[130:131]
	s_mov_b32 m0, s28
	s_nop 0
	global_load_lds_dwordx4 v[220:221], off
	v_lshl_add_u64 v[220:221], s[26:27], 0, v[134:135]
	s_add_i32 m0, s28, 0x2000
	s_nop 0
	global_load_lds_dwordx4 v[220:221], off
	v_lshl_add_u64 v[220:221], v[224:225], 0, s[10:11]
	s_mov_b32 m0, s39
	s_nop 0
	global_load_lds_dwordx4 v[220:221], off
	v_lshl_add_u64 v[220:221], v[226:227], 0, s[10:11]
	s_mov_b32 m0, s40
	s_nop 0
	global_load_lds_dwordx4 v[220:221], off
	s_waitcnt vmcnt(8)
	s_waitcnt lgkmcnt(0)
	s_barrier
	s_waitcnt lgkmcnt(0)
	v_mfma_f32_16x16x32_bf16 v[60:63], v[144:147], v[188:191], v[60:63]
	v_mfma_f32_16x16x32_bf16 v[56:59], v[160:163], v[188:191], v[56:59]
	v_mfma_f32_16x16x32_bf16 v[44:47], v[144:147], v[196:199], v[44:47]
	v_mfma_f32_16x16x32_bf16 v[40:43], v[160:163], v[196:199], v[40:43]
	v_mfma_f32_16x16x32_bf16 v[28:31], v[144:147], v[204:207], v[28:31]
	v_mfma_f32_16x16x32_bf16 v[24:27], v[160:163], v[204:207], v[24:27]
	v_mfma_f32_16x16x32_bf16 v[12:15], v[144:147], v[212:215], v[12:15]
	v_mfma_f32_16x16x32_bf16 v[8:11], v[160:163], v[212:215], v[8:11]
	v_mfma_f32_16x16x32_bf16 v[60:63], v[156:159], v[192:195], v[60:63]
	v_mfma_f32_16x16x32_bf16 v[56:59], v[164:167], v[192:195], v[56:59]
	v_mfma_f32_16x16x32_bf16 v[44:47], v[156:159], v[200:203], v[44:47]
	v_mfma_f32_16x16x32_bf16 v[40:43], v[164:167], v[200:203], v[40:43]
	v_mfma_f32_16x16x32_bf16 v[28:31], v[156:159], v[208:211], v[28:31]
	v_mfma_f32_16x16x32_bf16 v[24:27], v[164:167], v[208:211], v[24:27]
	v_mfma_f32_16x16x32_bf16 v[12:15], v[156:159], v[216:219], v[12:15]
	v_mfma_f32_16x16x32_bf16 v[8:11], v[164:167], v[216:219], v[8:11]
	v_mfma_f32_16x16x32_bf16 v[52:55], v[168:171], v[188:191], v[52:55]
	v_mfma_f32_16x16x32_bf16 v[48:51], v[176:179], v[188:191], v[48:51]
	v_mfma_f32_16x16x32_bf16 v[36:39], v[168:171], v[196:199], v[36:39]
	v_mfma_f32_16x16x32_bf16 v[32:35], v[176:179], v[196:199], v[32:35]
	v_mfma_f32_16x16x32_bf16 v[20:23], v[168:171], v[204:207], v[20:23]
	v_mfma_f32_16x16x32_bf16 v[16:19], v[176:179], v[204:207], v[16:19]
	v_mfma_f32_16x16x32_bf16 v[4:7], v[168:171], v[212:215], v[4:7]
	v_mfma_f32_16x16x32_bf16 v[0:3], v[176:179], v[212:215], v[0:3]
	v_mfma_f32_16x16x32_bf16 v[52:55], v[172:175], v[192:195], v[52:55]
	v_mfma_f32_16x16x32_bf16 v[48:51], v[184:187], v[192:195], v[48:51]
	v_mfma_f32_16x16x32_bf16 v[36:39], v[172:175], v[200:203], v[36:39]
	v_mfma_f32_16x16x32_bf16 v[32:35], v[184:187], v[200:203], v[32:35]
	v_mfma_f32_16x16x32_bf16 v[20:23], v[172:175], v[208:211], v[20:23]
	v_mfma_f32_16x16x32_bf16 v[16:19], v[184:187], v[208:211], v[16:19]
	v_mfma_f32_16x16x32_bf16 v[4:7], v[172:175], v[216:219], v[4:7]
	v_mfma_f32_16x16x32_bf16 v[0:3], v[184:187], v[216:219], v[0:3]
	s_barrier
	s_add_i32 s47, s47, 2
	s_add_u32 s24, s24, 0x100
	s_addc_u32 s25, s25, 0
	s_add_u32 s45, s45, 0x100
	s_addc_u32 s46, s46, 0
	s_cmp_gt_u32 s47, 13
	s_cbranch_scc0 .LBB0_1291
	s_and_b64 vcc, exec, s[12:13]
	s_cbranch_vccz .LBB0_1294
	s_barrier

.LBB0_1379:
	ds_read_b128 v[154:157], v151
	ds_read_b128 v[158:161], v151 offset:1024
	ds_read_b128 v[162:165], v151 offset:2048
	ds_read_b128 v[166:169], v151 offset:3072
	ds_read_b128 v[170:173], v152
	ds_read_b128 v[174:177], v152 offset:1024
	ds_read_b128 v[184:187], v152 offset:2048
	ds_read_b128 v[188:191], v152 offset:3072
	s_add_u32 s22, s20, 0xfffc0080
	s_addc_u32 s23, s21, -1
	s_cmp_eq_u32 s46, 12
	s_cselect_b32 s25, s13, s23
	s_cselect_b32 s24, s42, s22
	s_cselect_b32 s23, s11, s45
	s_cselect_b32 s22, s43, s44
	v_lshl_add_u64 v[178:179], s[20:21], 0, v[136:137]
	s_add_i32 m0, s19, 0xc000
	ds_read_b128 v[192:195], v153
	ds_read_b128 v[196:199], v153 offset:1024
	ds_read_b128 v[200:203], v153 offset:2048
	ds_read_b128 v[204:207], v153 offset:3072
	ds_read_b128 v[208:211], v153 offset:4096
	ds_read_b128 v[212:215], v153 offset:5120
	ds_read_b128 v[216:219], v153 offset:6144
	ds_read_b128 v[220:223], v153 offset:7168
	global_load_lds_dwordx4 v[178:179], off
	v_lshl_add_u64 v[178:179], s[20:21], 0, v[138:139]
	s_add_i32 m0, s19, 0xe000
	s_nop 0
	global_load_lds_dwordx4 v[178:179], off
	s_waitcnt vmcnt(8)
	s_waitcnt lgkmcnt(0)
	s_barrier
	s_waitcnt lgkmcnt(0)
	v_mfma_f32_16x16x32_bf16 v[124:127], v[154:157], v[192:195], v[124:127]
	v_mfma_f32_16x16x32_bf16 v[116:119], v[162:165], v[192:195], v[116:119]
	v_mfma_f32_16x16x32_bf16 v[108:111], v[154:157], v[200:203], v[108:111]
	v_mfma_f32_16x16x32_bf16 v[100:103], v[162:165], v[200:203], v[100:103]
	v_mfma_f32_16x16x32_bf16 v[92:95], v[154:157], v[208:211], v[92:95]
	v_mfma_f32_16x16x32_bf16 v[84:87], v[162:165], v[208:211], v[84:87]
	v_mfma_f32_16x16x32_bf16 v[76:79], v[154:157], v[216:219], v[76:79]
	v_mfma_f32_16x16x32_bf16 v[68:71], v[162:165], v[216:219], v[68:71]
	v_mfma_f32_16x16x32_bf16 v[124:127], v[158:161], v[196:199], v[124:127]
	v_mfma_f32_16x16x32_bf16 v[116:119], v[166:169], v[196:199], v[116:119]
	v_mfma_f32_16x16x32_bf16 v[108:111], v[158:161], v[204:207], v[108:111]
	v_mfma_f32_16x16x32_bf16 v[100:103], v[166:169], v[204:207], v[100:103]
	v_mfma_f32_16x16x32_bf16 v[92:95], v[158:161], v[212:215], v[92:95]
	v_mfma_f32_16x16x32_bf16 v[84:87], v[166:169], v[212:215], v[84:87]
	v_mfma_f32_16x16x32_bf16 v[76:79], v[158:161], v[220:223], v[76:79]
	v_mfma_f32_16x16x32_bf16 v[68:71], v[166:169], v[220:223], v[68:71]
	v_mfma_f32_16x16x32_bf16 v[120:123], v[170:173], v[192:195], v[120:123]
	v_mfma_f32_16x16x32_bf16 v[112:115], v[184:187], v[192:195], v[112:115]
	v_mfma_f32_16x16x32_bf16 v[104:107], v[170:173], v[200:203], v[104:107]
	v_mfma_f32_16x16x32_bf16 v[96:99], v[184:187], v[200:203], v[96:99]
	v_mfma_f32_16x16x32_bf16 v[88:91], v[170:173], v[208:211], v[88:91]
	v_mfma_f32_16x16x32_bf16 v[80:83], v[184:187], v[208:211], v[80:83]
	v_mfma_f32_16x16x32_bf16 v[72:75], v[170:173], v[216:219], v[72:75]
	v_mfma_f32_16x16x32_bf16 v[64:67], v[184:187], v[216:219], v[64:67]
	v_mfma_f32_16x16x32_bf16 v[120:123], v[174:177], v[196:199], v[120:123]
	v_mfma_f32_16x16x32_bf16 v[112:115], v[188:191], v[196:199], v[112:115]
	v_mfma_f32_16x16x32_bf16 v[104:107], v[174:177], v[204:207], v[104:107]
	v_mfma_f32_16x16x32_bf16 v[96:99], v[188:191], v[204:207], v[96:99]
	v_mfma_f32_16x16x32_bf16 v[88:91], v[174:177], v[212:215], v[88:91]
	v_mfma_f32_16x16x32_bf16 v[80:83], v[188:191], v[212:215], v[80:83]
	v_mfma_f32_16x16x32_bf16 v[72:75], v[174:177], v[220:223], v[72:75]
	v_mfma_f32_16x16x32_bf16 v[64:67], v[188:191], v[220:223], v[64:67]
	s_barrier
	s_add_i32 s47, s36, s28
	v_lshl_add_u64 v[178:179], s[22:23], 0, v[132:133]
	s_mov_b32 m0, s47
	ds_read_b128 v[192:195], v153 offset:16384
	ds_read_b128 v[196:199], v153 offset:17408
	ds_read_b128 v[200:203], v153 offset:18432
	ds_read_b128 v[204:207], v153 offset:19456
	ds_read_b128 v[208:211], v153 offset:20480
	ds_read_b128 v[212:215], v153 offset:21504
	ds_read_b128 v[216:219], v153 offset:22528
	ds_read_b128 v[220:223], v153 offset:23552
	global_load_lds_dwordx4 v[178:179], off
	s_add_i32 m0, s47, 0x2000
	s_add_u32 s48, s22, 0x40000
	v_lshl_add_u64 v[224:225], s[22:23], 0, v[128:129]
	s_addc_u32 s49, s23, 0
	s_add_i32 s47, s37, s28
	global_load_lds_dwordx4 v[224:225], off
	v_lshl_add_u64 v[226:227], s[48:49], 0, v[132:133]
	s_mov_b32 m0, s47
	v_lshl_add_u64 v[228:229], s[24:25], 0, v[130:131]
	global_load_lds_dwordx4 v[226:227], off
	v_lshl_add_u64 v[226:227], s[48:49], 0, v[128:129]
	s_add_i32 m0, s47, 0x2000
	s_nop 0
	global_load_lds_dwordx4 v[226:227], off
	v_lshl_add_u64 v[226:227], s[24:25], 0, v[134:135]
	s_mov_b32 m0, s19
	s_nop 0
	global_load_lds_dwordx4 v[226:227], off
	s_mov_b32 m0, s30
	s_nop 0
	global_load_lds_dwordx4 v[228:229], off
	s_waitcnt vmcnt(8)
	s_waitcnt lgkmcnt(0)
	s_barrier
	s_waitcnt lgkmcnt(0)
	v_mfma_f32_16x16x32_bf16 v[60:63], v[154:157], v[192:195], v[60:63]
	v_mfma_f32_16x16x32_bf16 v[52:55], v[162:165], v[192:195], v[52:55]
	v_mfma_f32_16x16x32_bf16 v[44:47], v[154:157], v[200:203], v[44:47]
	v_mfma_f32_16x16x32_bf16 v[36:39], v[162:165], v[200:203], v[36:39]
	v_mfma_f32_16x16x32_bf16 v[28:31], v[154:157], v[208:211], v[28:31]
	v_mfma_f32_16x16x32_bf16 v[20:23], v[162:165], v[208:211], v[20:23]
	v_mfma_f32_16x16x32_bf16 v[12:15], v[154:157], v[216:219], v[12:15]
	v_mfma_f32_16x16x32_bf16 v[4:7], v[162:165], v[216:219], v[4:7]
	v_mfma_f32_16x16x32_bf16 v[60:63], v[158:161], v[196:199], v[60:63]
	v_mfma_f32_16x16x32_bf16 v[52:55], v[166:169], v[196:199], v[52:55]
	v_mfma_f32_16x16x32_bf16 v[44:47], v[158:161], v[204:207], v[44:47]
	v_mfma_f32_16x16x32_bf16 v[36:39], v[166:169], v[204:207], v[36:39]
	v_mfma_f32_16x16x32_bf16 v[28:31], v[158:161], v[212:215], v[28:31]
	v_mfma_f32_16x16x32_bf16 v[20:23], v[166:169], v[212:215], v[20:23]
	v_mfma_f32_16x16x32_bf16 v[12:15], v[158:161], v[220:223], v[12:15]
	v_mfma_f32_16x16x32_bf16 v[4:7], v[166:169], v[220:223], v[4:7]
	v_mfma_f32_16x16x32_bf16 v[56:59], v[170:173], v[192:195], v[56:59]
	v_mfma_f32_16x16x32_bf16 v[48:51], v[184:187], v[192:195], v[48:51]
	v_mfma_f32_16x16x32_bf16 v[40:43], v[170:173], v[200:203], v[40:43]
	v_mfma_f32_16x16x32_bf16 v[32:35], v[184:187], v[200:203], v[32:35]
	v_mfma_f32_16x16x32_bf16 v[24:27], v[170:173], v[208:211], v[24:27]
	v_mfma_f32_16x16x32_bf16 v[16:19], v[184:187], v[208:211], v[16:19]
	v_mfma_f32_16x16x32_bf16 v[8:11], v[170:173], v[216:219], v[8:11]
	v_mfma_f32_16x16x32_bf16 v[0:3], v[184:187], v[216:219], v[0:3]
	v_mfma_f32_16x16x32_bf16 v[56:59], v[174:177], v[196:199], v[56:59]
	v_mfma_f32_16x16x32_bf16 v[48:51], v[188:191], v[196:199], v[48:51]
	v_mfma_f32_16x16x32_bf16 v[40:43], v[174:177], v[204:207], v[40:43]
	v_mfma_f32_16x16x32_bf16 v[32:35], v[188:191], v[204:207], v[32:35]
	v_mfma_f32_16x16x32_bf16 v[24:27], v[174:177], v[212:215], v[24:27]
	v_mfma_f32_16x16x32_bf16 v[16:19], v[188:191], v[212:215], v[16:19]
	v_mfma_f32_16x16x32_bf16 v[8:11], v[174:177], v[220:223], v[8:11]
	v_mfma_f32_16x16x32_bf16 v[0:3], v[188:191], v[220:223], v[0:3]
	s_barrier
	s_add_i32 s47, 0, 0x18000
	s_add_i32 s48, 0, 0x1c000
	v_add_u32_e32 v166, s47, v145
	v_add_u32_e32 v180, s48, v145
	ds_read_b128 v[154:157], v166
	ds_read_b128 v[158:161], v166 offset:1024
	ds_read_b128 v[162:165], v166 offset:2048
	ds_read_b128 v[166:169], v166 offset:3072
	ds_read_b128 v[170:173], v180
	ds_read_b128 v[174:177], v180 offset:1024
	ds_read_b128 v[184:187], v180 offset:2048
	ds_read_b128 v[188:191], v180 offset:3072
	s_add_u32 s24, s24, 0x40000
	s_addc_u32 s25, s25, 0
	s_mov_b32 m0, s31
	v_lshl_add_u64 v[230:231], s[24:25], 0, v[134:135]
	ds_read_b128 v[192:195], v153 offset:32768
	ds_read_b128 v[196:199], v153 offset:33792
	ds_read_b128 v[200:203], v153 offset:34816
	ds_read_b128 v[204:207], v153 offset:35840
	ds_read_b128 v[208:211], v153 offset:36864
	ds_read_b128 v[212:215], v153 offset:37888
	ds_read_b128 v[216:219], v153 offset:38912
	ds_read_b128 v[220:223], v153 offset:39936
	global_load_lds_dwordx4 v[230:231], off
	v_lshl_add_u64 v[230:231], s[24:25], 0, v[130:131]
	s_mov_b32 m0, s33
	s_nop 0
	global_load_lds_dwordx4 v[230:231], off
	s_waitcnt vmcnt(8)
	s_waitcnt lgkmcnt(0)
	s_barrier
	s_waitcnt lgkmcnt(0)
	v_mfma_f32_16x16x32_bf16 v[124:127], v[154:157], v[192:195], v[124:127]
	v_mfma_f32_16x16x32_bf16 v[116:119], v[162:165], v[192:195], v[116:119]
	v_mfma_f32_16x16x32_bf16 v[108:111], v[154:157], v[200:203], v[108:111]
	v_mfma_f32_16x16x32_bf16 v[100:103], v[162:165], v[200:203], v[100:103]
	v_mfma_f32_16x16x32_bf16 v[92:95], v[154:157], v[208:211], v[92:95]
	v_mfma_f32_16x16x32_bf16 v[84:87], v[162:165], v[208:211], v[84:87]
	v_mfma_f32_16x16x32_bf16 v[76:79], v[154:157], v[216:219], v[76:79]
	v_mfma_f32_16x16x32_bf16 v[68:71], v[162:165], v[216:219], v[68:71]
	v_mfma_f32_16x16x32_bf16 v[124:127], v[158:161], v[196:199], v[124:127]
	v_mfma_f32_16x16x32_bf16 v[116:119], v[166:169], v[196:199], v[116:119]
	v_mfma_f32_16x16x32_bf16 v[108:111], v[158:161], v[204:207], v[108:111]
	v_mfma_f32_16x16x32_bf16 v[100:103], v[166:169], v[204:207], v[100:103]
	v_mfma_f32_16x16x32_bf16 v[92:95], v[158:161], v[212:215], v[92:95]
	v_mfma_f32_16x16x32_bf16 v[84:87], v[166:169], v[212:215], v[84:87]
	v_mfma_f32_16x16x32_bf16 v[76:79], v[158:161], v[220:223], v[76:79]
	v_mfma_f32_16x16x32_bf16 v[68:71], v[166:169], v[220:223], v[68:71]
	v_mfma_f32_16x16x32_bf16 v[120:123], v[170:173], v[192:195], v[120:123]
	v_mfma_f32_16x16x32_bf16 v[112:115], v[184:187], v[192:195], v[112:115]
	v_mfma_f32_16x16x32_bf16 v[104:107], v[170:173], v[200:203], v[104:107]
	v_mfma_f32_16x16x32_bf16 v[96:99], v[184:187], v[200:203], v[96:99]
	v_mfma_f32_16x16x32_bf16 v[88:91], v[170:173], v[208:211], v[88:91]
	v_mfma_f32_16x16x32_bf16 v[80:83], v[184:187], v[208:211], v[80:83]
	v_mfma_f32_16x16x32_bf16 v[72:75], v[170:173], v[216:219], v[72:75]
	v_mfma_f32_16x16x32_bf16 v[64:67], v[184:187], v[216:219], v[64:67]
	v_mfma_f32_16x16x32_bf16 v[120:123], v[174:177], v[196:199], v[120:123]
	v_mfma_f32_16x16x32_bf16 v[112:115], v[188:191], v[196:199], v[112:115]
	v_mfma_f32_16x16x32_bf16 v[104:107], v[174:177], v[204:207], v[104:107]
	v_mfma_f32_16x16x32_bf16 v[96:99], v[188:191], v[204:207], v[96:99]
	v_mfma_f32_16x16x32_bf16 v[88:91], v[174:177], v[212:215], v[88:91]
	v_mfma_f32_16x16x32_bf16 v[80:83], v[188:191], v[212:215], v[80:83]
	v_mfma_f32_16x16x32_bf16 v[72:75], v[174:177], v[220:223], v[72:75]
	v_mfma_f32_16x16x32_bf16 v[64:67], v[188:191], v[220:223], v[64:67]
	s_barrier
	s_add_i32 s24, s47, s28
	v_lshl_add_u64 v[178:179], v[178:179], 0, s[6:7]
	s_mov_b32 m0, s24
	ds_read_b128 v[192:195], v153 offset:49152
	ds_read_b128 v[196:199], v153 offset:50176
	ds_read_b128 v[200:203], v153 offset:51200
	ds_read_b128 v[204:207], v153 offset:52224
	ds_read_b128 v[208:211], v153 offset:53248
	ds_read_b128 v[212:215], v153 offset:54272
	ds_read_b128 v[216:219], v153 offset:55296
	ds_read_b128 v[220:223], v153 offset:56320
	global_load_lds_dwordx4 v[178:179], off
	s_add_i32 m0, s24, 0x2000
	s_add_u32 s22, s22, 0x40080
	v_lshl_add_u64 v[178:179], v[224:225], 0, s[6:7]
	s_addc_u32 s23, s23, 0
	s_add_i32 s24, s48, s28
	global_load_lds_dwordx4 v[178:179], off
	v_lshl_add_u64 v[178:179], s[22:23], 0, v[132:133]
	s_mov_b32 m0, s24
	s_nop 0
	global_load_lds_dwordx4 v[178:179], off
	v_lshl_add_u64 v[178:179], s[22:23], 0, v[128:129]
	s_add_i32 m0, s24, 0x2000
	s_nop 0
	global_load_lds_dwordx4 v[178:179], off
	v_lshl_add_u64 v[178:179], v[226:227], 0, s[6:7]
	s_mov_b32 m0, s34
	s_nop 0
	global_load_lds_dwordx4 v[178:179], off
	v_lshl_add_u64 v[178:179], v[228:229], 0, s[6:7]
	s_mov_b32 m0, s35
	s_nop 0
	global_load_lds_dwordx4 v[178:179], off
	s_waitcnt vmcnt(8)
	s_waitcnt lgkmcnt(0)
	s_barrier
	s_waitcnt lgkmcnt(0)
	v_mfma_f32_16x16x32_bf16 v[60:63], v[154:157], v[192:195], v[60:63]
	v_mfma_f32_16x16x32_bf16 v[52:55], v[162:165], v[192:195], v[52:55]
	v_mfma_f32_16x16x32_bf16 v[44:47], v[154:157], v[200:203], v[44:47]
	v_mfma_f32_16x16x32_bf16 v[36:39], v[162:165], v[200:203], v[36:39]
	v_mfma_f32_16x16x32_bf16 v[28:31], v[154:157], v[208:211], v[28:31]
	v_mfma_f32_16x16x32_bf16 v[20:23], v[162:165], v[208:211], v[20:23]
	v_mfma_f32_16x16x32_bf16 v[12:15], v[154:157], v[216:219], v[12:15]
	v_mfma_f32_16x16x32_bf16 v[4:7], v[162:165], v[216:219], v[4:7]
	v_mfma_f32_16x16x32_bf16 v[60:63], v[158:161], v[196:199], v[60:63]
	v_mfma_f32_16x16x32_bf16 v[52:55], v[166:169], v[196:199], v[52:55]
	v_mfma_f32_16x16x32_bf16 v[44:47], v[158:161], v[204:207], v[44:47]
	v_mfma_f32_16x16x32_bf16 v[36:39], v[166:169], v[204:207], v[36:39]
	v_mfma_f32_16x16x32_bf16 v[28:31], v[158:161], v[212:215], v[28:31]
	v_mfma_f32_16x16x32_bf16 v[20:23], v[166:169], v[212:215], v[20:23]
	v_mfma_f32_16x16x32_bf16 v[12:15], v[158:161], v[220:223], v[12:15]
	v_mfma_f32_16x16x32_bf16 v[4:7], v[166:169], v[220:223], v[4:7]
	v_mfma_f32_16x16x32_bf16 v[56:59], v[170:173], v[192:195], v[56:59]
	v_mfma_f32_16x16x32_bf16 v[48:51], v[184:187], v[192:195], v[48:51]
	v_mfma_f32_16x16x32_bf16 v[40:43], v[170:173], v[200:203], v[40:43]
	v_mfma_f32_16x16x32_bf16 v[32:35], v[184:187], v[200:203], v[32:35]
	v_mfma_f32_16x16x32_bf16 v[24:27], v[170:173], v[208:211], v[24:27]
	v_mfma_f32_16x16x32_bf16 v[16:19], v[184:187], v[208:211], v[16:19]
	v_mfma_f32_16x16x32_bf16 v[8:11], v[170:173], v[216:219], v[8:11]
	v_mfma_f32_16x16x32_bf16 v[0:3], v[184:187], v[216:219], v[0:3]
	v_mfma_f32_16x16x32_bf16 v[56:59], v[174:177], v[196:199], v[56:59]
	v_mfma_f32_16x16x32_bf16 v[48:51], v[188:191], v[196:199], v[48:51]
	v_mfma_f32_16x16x32_bf16 v[40:43], v[174:177], v[204:207], v[40:43]
	v_mfma_f32_16x16x32_bf16 v[32:35], v[188:191], v[204:207], v[32:35]
	v_mfma_f32_16x16x32_bf16 v[24:27], v[174:177], v[212:215], v[24:27]
	v_mfma_f32_16x16x32_bf16 v[16:19], v[188:191], v[212:215], v[16:19]
	v_mfma_f32_16x16x32_bf16 v[8:11], v[174:177], v[220:223], v[8:11]
	v_mfma_f32_16x16x32_bf16 v[0:3], v[188:191], v[220:223], v[0:3]
	s_barrier
	s_add_i32 s46, s46, 2
	s_add_u32 s20, s20, 0x100
	s_addc_u32 s21, s21, 0
	s_add_u32 s44, s44, 0x100
	s_addc_u32 s45, s45, 0
	s_cmp_gt_u32 s46, 13
	s_cbranch_scc0 .LBB0_1379
	s_and_b64 vcc, exec, s[8:9]
	s_cbranch_vccz .LBB0_1382
	s_barrier

.LBB0_1461:
	ds_read_b128 v[144:147], v151
	ds_read_b128 v[156:159], v151 offset:1024
	ds_read_b128 v[160:163], v151 offset:2048
	ds_read_b128 v[164:167], v151 offset:3072
	ds_read_b128 v[168:171], v152
	ds_read_b128 v[172:175], v152 offset:1024
	ds_read_b128 v[176:179], v152 offset:2048
	ds_read_b128 v[182:185], v152 offset:3072
	s_add_u32 s20, s18, 0x100
	s_addc_u32 s21, s19, 0
	s_cmp_eq_u32 s45, 40
	s_cselect_b32 s25, s7, s21
	s_cselect_b32 s24, s6, s20
	s_cselect_b32 s23, s17, s44
	s_cselect_b32 s22, s16, s43
	v_lshl_add_u64 v[218:219], s[18:19], 0, v[136:137]
	s_add_i32 m0, s29, 0xc000
	ds_read_b128 v[186:189], v153
	ds_read_b128 v[190:193], v153 offset:1024
	ds_read_b128 v[194:197], v153 offset:2048
	ds_read_b128 v[198:201], v153 offset:3072
	ds_read_b128 v[202:205], v153 offset:4096
	ds_read_b128 v[206:209], v153 offset:5120
	ds_read_b128 v[210:213], v153 offset:6144
	ds_read_b128 v[214:217], v153 offset:7168
	global_load_lds_dwordx4 v[218:219], off
	v_lshl_add_u64 v[218:219], s[18:19], 0, v[138:139]
	s_add_i32 m0, s29, 0xe000
	s_nop 0
	global_load_lds_dwordx4 v[218:219], off
	s_waitcnt vmcnt(8)
	s_waitcnt lgkmcnt(0)
	s_barrier
	s_waitcnt lgkmcnt(0)
	v_mfma_f32_16x16x32_bf16 v[124:127], v[144:147], v[186:189], v[124:127]
	v_mfma_f32_16x16x32_bf16 v[120:123], v[160:163], v[186:189], v[120:123]
	v_mfma_f32_16x16x32_bf16 v[108:111], v[144:147], v[194:197], v[108:111]
	v_mfma_f32_16x16x32_bf16 v[104:107], v[160:163], v[194:197], v[104:107]
	v_mfma_f32_16x16x32_bf16 v[92:95], v[144:147], v[202:205], v[92:95]
	v_mfma_f32_16x16x32_bf16 v[88:91], v[160:163], v[202:205], v[88:91]
	v_mfma_f32_16x16x32_bf16 v[76:79], v[144:147], v[210:213], v[76:79]
	v_mfma_f32_16x16x32_bf16 v[72:75], v[160:163], v[210:213], v[72:75]
	v_mfma_f32_16x16x32_bf16 v[124:127], v[156:159], v[190:193], v[124:127]
	v_mfma_f32_16x16x32_bf16 v[120:123], v[164:167], v[190:193], v[120:123]
	v_mfma_f32_16x16x32_bf16 v[108:111], v[156:159], v[198:201], v[108:111]
	v_mfma_f32_16x16x32_bf16 v[104:107], v[164:167], v[198:201], v[104:107]
	v_mfma_f32_16x16x32_bf16 v[92:95], v[156:159], v[206:209], v[92:95]
	v_mfma_f32_16x16x32_bf16 v[88:91], v[164:167], v[206:209], v[88:91]
	v_mfma_f32_16x16x32_bf16 v[76:79], v[156:159], v[214:217], v[76:79]
	v_mfma_f32_16x16x32_bf16 v[72:75], v[164:167], v[214:217], v[72:75]
	v_mfma_f32_16x16x32_bf16 v[116:119], v[168:171], v[186:189], v[116:119]
	v_mfma_f32_16x16x32_bf16 v[112:115], v[176:179], v[186:189], v[112:115]
	v_mfma_f32_16x16x32_bf16 v[100:103], v[168:171], v[194:197], v[100:103]
	v_mfma_f32_16x16x32_bf16 v[96:99], v[176:179], v[194:197], v[96:99]
	v_mfma_f32_16x16x32_bf16 v[84:87], v[168:171], v[202:205], v[84:87]
	v_mfma_f32_16x16x32_bf16 v[80:83], v[176:179], v[202:205], v[80:83]
	v_mfma_f32_16x16x32_bf16 v[68:71], v[168:171], v[210:213], v[68:71]
	v_mfma_f32_16x16x32_bf16 v[64:67], v[176:179], v[210:213], v[64:67]
	v_mfma_f32_16x16x32_bf16 v[116:119], v[172:175], v[190:193], v[116:119]
	v_mfma_f32_16x16x32_bf16 v[112:115], v[182:185], v[190:193], v[112:115]
	v_mfma_f32_16x16x32_bf16 v[100:103], v[172:175], v[198:201], v[100:103]
	v_mfma_f32_16x16x32_bf16 v[96:99], v[182:185], v[198:201], v[96:99]
	v_mfma_f32_16x16x32_bf16 v[84:87], v[172:175], v[206:209], v[84:87]
	v_mfma_f32_16x16x32_bf16 v[80:83], v[182:185], v[206:209], v[80:83]
	v_mfma_f32_16x16x32_bf16 v[68:71], v[172:175], v[214:217], v[68:71]
	v_mfma_f32_16x16x32_bf16 v[64:67], v[182:185], v[214:217], v[64:67]
	s_barrier
	s_add_i32 s18, s37, s28
	v_lshl_add_u64 v[218:219], s[22:23], 0, v[130:131]
	s_mov_b32 m0, s18
	ds_read_b128 v[186:189], v153 offset:16384
	ds_read_b128 v[190:193], v153 offset:17408
	ds_read_b128 v[194:197], v153 offset:18432
	ds_read_b128 v[198:201], v153 offset:19456
	ds_read_b128 v[202:205], v153 offset:20480
	ds_read_b128 v[206:209], v153 offset:21504
	ds_read_b128 v[210:213], v153 offset:22528
	ds_read_b128 v[214:217], v153 offset:23552
	global_load_lds_dwordx4 v[218:219], off
	s_add_i32 m0, s18, 0x2000
	s_add_u32 s18, s22, 0xb0000
	v_lshl_add_u64 v[220:221], s[22:23], 0, v[134:135]
	s_addc_u32 s19, s23, 0
	s_add_i32 s46, s38, s28
	global_load_lds_dwordx4 v[220:221], off
	v_lshl_add_u64 v[222:223], s[18:19], 0, v[130:131]
	s_mov_b32 m0, s46
	v_lshl_add_u64 v[224:225], s[24:25], 0, v[132:133]
	global_load_lds_dwordx4 v[222:223], off
	v_lshl_add_u64 v[222:223], s[18:19], 0, v[134:135]
	s_add_i32 m0, s46, 0x2000
	s_nop 0
	global_load_lds_dwordx4 v[222:223], off
	v_lshl_add_u64 v[222:223], s[24:25], 0, v[128:129]
	s_mov_b32 m0, s29
	s_nop 0
	global_load_lds_dwordx4 v[222:223], off
	s_mov_b32 m0, s30
	s_nop 0
	global_load_lds_dwordx4 v[224:225], off
	s_waitcnt vmcnt(8)
	s_waitcnt lgkmcnt(0)
	s_barrier
	s_waitcnt lgkmcnt(0)
	v_mfma_f32_16x16x32_bf16 v[60:63], v[144:147], v[186:189], v[60:63]
	v_mfma_f32_16x16x32_bf16 v[56:59], v[160:163], v[186:189], v[56:59]
	v_mfma_f32_16x16x32_bf16 v[44:47], v[144:147], v[194:197], v[44:47]
	v_mfma_f32_16x16x32_bf16 v[40:43], v[160:163], v[194:197], v[40:43]
	v_mfma_f32_16x16x32_bf16 v[28:31], v[144:147], v[202:205], v[28:31]
	v_mfma_f32_16x16x32_bf16 v[24:27], v[160:163], v[202:205], v[24:27]
	v_mfma_f32_16x16x32_bf16 v[12:15], v[144:147], v[210:213], v[12:15]
	v_mfma_f32_16x16x32_bf16 v[8:11], v[160:163], v[210:213], v[8:11]
	v_mfma_f32_16x16x32_bf16 v[60:63], v[156:159], v[190:193], v[60:63]
	v_mfma_f32_16x16x32_bf16 v[56:59], v[164:167], v[190:193], v[56:59]
	v_mfma_f32_16x16x32_bf16 v[44:47], v[156:159], v[198:201], v[44:47]
	v_mfma_f32_16x16x32_bf16 v[40:43], v[164:167], v[198:201], v[40:43]
	v_mfma_f32_16x16x32_bf16 v[28:31], v[156:159], v[206:209], v[28:31]
	v_mfma_f32_16x16x32_bf16 v[24:27], v[164:167], v[206:209], v[24:27]
	v_mfma_f32_16x16x32_bf16 v[12:15], v[156:159], v[214:217], v[12:15]
	v_mfma_f32_16x16x32_bf16 v[8:11], v[164:167], v[214:217], v[8:11]
	v_mfma_f32_16x16x32_bf16 v[52:55], v[168:171], v[186:189], v[52:55]
	v_mfma_f32_16x16x32_bf16 v[48:51], v[176:179], v[186:189], v[48:51]
	v_mfma_f32_16x16x32_bf16 v[36:39], v[168:171], v[194:197], v[36:39]
	v_mfma_f32_16x16x32_bf16 v[32:35], v[176:179], v[194:197], v[32:35]
	v_mfma_f32_16x16x32_bf16 v[20:23], v[168:171], v[202:205], v[20:23]
	v_mfma_f32_16x16x32_bf16 v[16:19], v[176:179], v[202:205], v[16:19]
	v_mfma_f32_16x16x32_bf16 v[4:7], v[168:171], v[210:213], v[4:7]
	v_mfma_f32_16x16x32_bf16 v[0:3], v[176:179], v[210:213], v[0:3]
	v_mfma_f32_16x16x32_bf16 v[52:55], v[172:175], v[190:193], v[52:55]
	v_mfma_f32_16x16x32_bf16 v[48:51], v[182:185], v[190:193], v[48:51]
	v_mfma_f32_16x16x32_bf16 v[36:39], v[172:175], v[198:201], v[36:39]
	v_mfma_f32_16x16x32_bf16 v[32:35], v[182:185], v[198:201], v[32:35]
	v_mfma_f32_16x16x32_bf16 v[20:23], v[172:175], v[206:209], v[20:23]
	v_mfma_f32_16x16x32_bf16 v[16:19], v[182:185], v[206:209], v[16:19]
	v_mfma_f32_16x16x32_bf16 v[4:7], v[172:175], v[214:217], v[4:7]
	v_mfma_f32_16x16x32_bf16 v[0:3], v[182:185], v[214:217], v[0:3]
	s_barrier
	s_add_i32 s46, 0, 0x18000
	v_add_u32_e32 v155, s46, v149
	s_add_i32 s47, 0, 0x1c000
	ds_read_b128 v[144:147], v155
	ds_read_b128 v[156:159], v155 offset:1024
	ds_read_b128 v[160:163], v155 offset:2048
	ds_read_b128 v[164:167], v155 offset:3072
	v_add_u32_e32 v155, s47, v149
	ds_read_b128 v[168:171], v155
	ds_read_b128 v[172:175], v155 offset:1024
	ds_read_b128 v[176:179], v155 offset:2048
	ds_read_b128 v[182:185], v155 offset:3072
	s_add_u32 s18, s24, 0xb0000
	s_addc_u32 s19, s25, 0
	s_mov_b32 m0, s31
	v_lshl_add_u64 v[226:227], s[18:19], 0, v[128:129]
	ds_read_b128 v[186:189], v153 offset:32768
	ds_read_b128 v[190:193], v153 offset:33792
	ds_read_b128 v[194:197], v153 offset:34816
	ds_read_b128 v[198:201], v153 offset:35840
	ds_read_b128 v[202:205], v153 offset:36864
	ds_read_b128 v[206:209], v153 offset:37888
	ds_read_b128 v[210:213], v153 offset:38912
	ds_read_b128 v[214:217], v153 offset:39936
	global_load_lds_dwordx4 v[226:227], off
	v_lshl_add_u64 v[226:227], s[18:19], 0, v[132:133]
	s_mov_b32 m0, s33
	s_nop 0
	global_load_lds_dwordx4 v[226:227], off
	s_waitcnt vmcnt(8)
	s_waitcnt lgkmcnt(0)
	s_barrier
	s_waitcnt lgkmcnt(0)
	v_mfma_f32_16x16x32_bf16 v[124:127], v[144:147], v[186:189], v[124:127]
	v_mfma_f32_16x16x32_bf16 v[120:123], v[160:163], v[186:189], v[120:123]
	v_mfma_f32_16x16x32_bf16 v[108:111], v[144:147], v[194:197], v[108:111]
	v_mfma_f32_16x16x32_bf16 v[104:107], v[160:163], v[194:197], v[104:107]
	v_mfma_f32_16x16x32_bf16 v[92:95], v[144:147], v[202:205], v[92:95]
	v_mfma_f32_16x16x32_bf16 v[88:91], v[160:163], v[202:205], v[88:91]
	v_mfma_f32_16x16x32_bf16 v[76:79], v[144:147], v[210:213], v[76:79]
	v_mfma_f32_16x16x32_bf16 v[72:75], v[160:163], v[210:213], v[72:75]
	v_mfma_f32_16x16x32_bf16 v[124:127], v[156:159], v[190:193], v[124:127]
	v_mfma_f32_16x16x32_bf16 v[120:123], v[164:167], v[190:193], v[120:123]
	v_mfma_f32_16x16x32_bf16 v[108:111], v[156:159], v[198:201], v[108:111]
	v_mfma_f32_16x16x32_bf16 v[104:107], v[164:167], v[198:201], v[104:107]
	v_mfma_f32_16x16x32_bf16 v[92:95], v[156:159], v[206:209], v[92:95]
	v_mfma_f32_16x16x32_bf16 v[88:91], v[164:167], v[206:209], v[88:91]
	v_mfma_f32_16x16x32_bf16 v[76:79], v[156:159], v[214:217], v[76:79]
	v_mfma_f32_16x16x32_bf16 v[72:75], v[164:167], v[214:217], v[72:75]
	v_mfma_f32_16x16x32_bf16 v[116:119], v[168:171], v[186:189], v[116:119]
	v_mfma_f32_16x16x32_bf16 v[112:115], v[176:179], v[186:189], v[112:115]
	v_mfma_f32_16x16x32_bf16 v[100:103], v[168:171], v[194:197], v[100:103]
	v_mfma_f32_16x16x32_bf16 v[96:99], v[176:179], v[194:197], v[96:99]
	v_mfma_f32_16x16x32_bf16 v[84:87], v[168:171], v[202:205], v[84:87]
	v_mfma_f32_16x16x32_bf16 v[80:83], v[176:179], v[202:205], v[80:83]
	v_mfma_f32_16x16x32_bf16 v[68:71], v[168:171], v[210:213], v[68:71]
	v_mfma_f32_16x16x32_bf16 v[64:67], v[176:179], v[210:213], v[64:67]
	v_mfma_f32_16x16x32_bf16 v[116:119], v[172:175], v[190:193], v[116:119]
	v_mfma_f32_16x16x32_bf16 v[112:115], v[182:185], v[190:193], v[112:115]
	v_mfma_f32_16x16x32_bf16 v[100:103], v[172:175], v[198:201], v[100:103]
	v_mfma_f32_16x16x32_bf16 v[96:99], v[182:185], v[198:201], v[96:99]
	v_mfma_f32_16x16x32_bf16 v[84:87], v[172:175], v[206:209], v[84:87]
	v_mfma_f32_16x16x32_bf16 v[80:83], v[182:185], v[206:209], v[80:83]
	v_mfma_f32_16x16x32_bf16 v[68:71], v[172:175], v[214:217], v[68:71]
	v_mfma_f32_16x16x32_bf16 v[64:67], v[182:185], v[214:217], v[64:67]
	s_barrier
	s_add_i32 s18, s46, s28
	v_lshl_add_u64 v[218:219], v[218:219], 0, s[12:13]
	s_mov_b32 m0, s18
	ds_read_b128 v[186:189], v153 offset:49152
	ds_read_b128 v[190:193], v153 offset:50176
	ds_read_b128 v[194:197], v153 offset:51200
	ds_read_b128 v[198:201], v153 offset:52224
	ds_read_b128 v[202:205], v153 offset:53248
	ds_read_b128 v[206:209], v153 offset:54272
	ds_read_b128 v[210:213], v153 offset:55296
	ds_read_b128 v[214:217], v153 offset:56320
	global_load_lds_dwordx4 v[218:219], off
	s_add_i32 m0, s18, 0x2000
	s_add_u32 s18, s22, 0xb0080
	v_lshl_add_u64 v[218:219], v[220:221], 0, s[12:13]
	s_addc_u32 s19, s23, 0
	s_add_i32 s22, s47, s28
	global_load_lds_dwordx4 v[218:219], off
	v_lshl_add_u64 v[218:219], s[18:19], 0, v[130:131]
	s_mov_b32 m0, s22
	s_nop 0
	global_load_lds_dwordx4 v[218:219], off
	v_lshl_add_u64 v[218:219], s[18:19], 0, v[134:135]
	s_add_i32 m0, s22, 0x2000
	s_nop 0
	global_load_lds_dwordx4 v[218:219], off
	v_lshl_add_u64 v[218:219], v[222:223], 0, s[12:13]
	s_mov_b32 m0, s35
	s_nop 0
	global_load_lds_dwordx4 v[218:219], off
	v_lshl_add_u64 v[218:219], v[224:225], 0, s[12:13]
	s_mov_b32 m0, s36
	s_nop 0
	global_load_lds_dwordx4 v[218:219], off
	s_waitcnt vmcnt(8)
	s_waitcnt lgkmcnt(0)
	s_barrier
	s_waitcnt lgkmcnt(0)
	v_mfma_f32_16x16x32_bf16 v[60:63], v[144:147], v[186:189], v[60:63]
	v_mfma_f32_16x16x32_bf16 v[56:59], v[160:163], v[186:189], v[56:59]
	v_mfma_f32_16x16x32_bf16 v[44:47], v[144:147], v[194:197], v[44:47]
	v_mfma_f32_16x16x32_bf16 v[40:43], v[160:163], v[194:197], v[40:43]
	v_mfma_f32_16x16x32_bf16 v[28:31], v[144:147], v[202:205], v[28:31]
	v_mfma_f32_16x16x32_bf16 v[24:27], v[160:163], v[202:205], v[24:27]
	v_mfma_f32_16x16x32_bf16 v[12:15], v[144:147], v[210:213], v[12:15]
	v_mfma_f32_16x16x32_bf16 v[8:11], v[160:163], v[210:213], v[8:11]
	v_mfma_f32_16x16x32_bf16 v[60:63], v[156:159], v[190:193], v[60:63]
	v_mfma_f32_16x16x32_bf16 v[56:59], v[164:167], v[190:193], v[56:59]
	v_mfma_f32_16x16x32_bf16 v[44:47], v[156:159], v[198:201], v[44:47]
	v_mfma_f32_16x16x32_bf16 v[40:43], v[164:167], v[198:201], v[40:43]
	v_mfma_f32_16x16x32_bf16 v[28:31], v[156:159], v[206:209], v[28:31]
	v_mfma_f32_16x16x32_bf16 v[24:27], v[164:167], v[206:209], v[24:27]
	v_mfma_f32_16x16x32_bf16 v[12:15], v[156:159], v[214:217], v[12:15]
	v_mfma_f32_16x16x32_bf16 v[8:11], v[164:167], v[214:217], v[8:11]
	v_mfma_f32_16x16x32_bf16 v[52:55], v[168:171], v[186:189], v[52:55]
	v_mfma_f32_16x16x32_bf16 v[48:51], v[176:179], v[186:189], v[48:51]
	v_mfma_f32_16x16x32_bf16 v[36:39], v[168:171], v[194:197], v[36:39]
	v_mfma_f32_16x16x32_bf16 v[32:35], v[176:179], v[194:197], v[32:35]
	v_mfma_f32_16x16x32_bf16 v[20:23], v[168:171], v[202:205], v[20:23]
	v_mfma_f32_16x16x32_bf16 v[16:19], v[176:179], v[202:205], v[16:19]
	v_mfma_f32_16x16x32_bf16 v[4:7], v[168:171], v[210:213], v[4:7]
	v_mfma_f32_16x16x32_bf16 v[0:3], v[176:179], v[210:213], v[0:3]
	v_mfma_f32_16x16x32_bf16 v[52:55], v[172:175], v[190:193], v[52:55]
	v_mfma_f32_16x16x32_bf16 v[48:51], v[182:185], v[190:193], v[48:51]
	v_mfma_f32_16x16x32_bf16 v[36:39], v[172:175], v[198:201], v[36:39]
	v_mfma_f32_16x16x32_bf16 v[32:35], v[182:185], v[198:201], v[32:35]
	v_mfma_f32_16x16x32_bf16 v[20:23], v[172:175], v[206:209], v[20:23]
	v_mfma_f32_16x16x32_bf16 v[16:19], v[182:185], v[206:209], v[16:19]
	v_mfma_f32_16x16x32_bf16 v[4:7], v[172:175], v[214:217], v[4:7]
	v_mfma_f32_16x16x32_bf16 v[0:3], v[182:185], v[214:217], v[0:3]
	s_barrier
	s_add_i32 s45, s45, 2
	s_add_u32 s43, s43, 0x100
	s_addc_u32 s44, s44, 0
	s_cmp_gt_u32 s45, 41
	s_mov_b64 s[18:19], s[20:21]
	s_cbranch_scc0 .LBB0_1461
	s_and_b64 vcc, exec, s[14:15]
	s_cbranch_vccz .LBB0_1464
	s_barrier
